# sparse attention: V row offsets published at unit start and the first 16 V row loads issued right after the last K group, before the softmax
# baseline (speedup 1.0000x reference)
; __device__ __forceinline__ void sparse_unit7(const bf16_t* QKV, const unsigned char* K8, const unsigned char* V8, const int (&selv)[4], bf16_t* OB, LAS unsigned char* wl, int t, int h, int lane) {
;     ...
;     const bf16_t* qrow = QKV + (size_t)t * QKVW + COL_BQ + h * 128 + 16 * slab;
;     long qa[4];
; #pragma unroll
;     for (int ks = 0; ks < 4; ++ks) { const u32x4 raw = *(const u32x4*)(qrow + 8 * (ks & 1) + 64 * (ks >> 1)); const unsigned w[4] = {raw.x, raw.y, raw.z, raw.w}; float x[8];
; #pragma unroll
;         for (int i = 0; i < 4; ++i) { x[2 * i] = bf2f(w[i] & 0xffffu); x[2 * i + 1] = __builtin_bit_cast(float, w[i] & 0xffff0000u); }
;         const u32x2 f = to_fp8x8(x); qa[ks] = (long)(((unsigned long long)f.y << 32) | f.x); }
;     const unsigned char* K8h = K8 + h * 128; const unsigned char* V8h = V8 + h * 128;
;     const int n = min(256, t + 1), ns = (n + 63) >> 6;
; #pragma unroll
;     for (int s = 0; s < 4; ++s) { const int j = 64 * s + lane; const int id = (j < n) ? selv[s] : 0; wsel[j] = id; otw[j] = (unsigned)id * 1024u; }
;     asm volatile("" ::: "memory");
;     long kf[16]; unsigned va[8], vb[8];
;     s8_issue_k(kf, K8h, wsel, 0, n16, slab);
; __global__ void __launch_bounds__(NTHREADS, 2) mega(Args a) {
;     ...
;                     for (int t = qg; t < SEQ; t += nqg) { int selc[4];
; #pragma unroll
;                         for (int s = 0; s < 4; ++s) selc[s] = seln[s];
;                         const int tn = min(t + nqg, SEQ - 1);
; #pragma unroll
;                         for (int s = 0; s < 4; ++s) seln[s] = (int)SEL[(size_t)tn * 256 + 64 * s + lane];
;                         sparse_unit7(QKV, K8, V8, selc, OB, lds + wave * 4096, t, h, lane); } }
.Lsp_unit:
	s_waitcnt vmcnt(1)
	s_add_i32 s98, s34, 1
	s_min_i32 s98, s98, 0x100
	v_and_b32_e32 v218, 0x3fff, v96
	v_lshl_add_u32 v218, v218, 7, v202
	global_load_dwordx4 v[0:3], v218, s[42:43]
	v_bfe_u32 v218, v96, 16, 14
	v_lshl_add_u32 v218, v218, 7, v202
	global_load_dwordx4 v[4:7], v218, s[42:43]
	v_and_b32_e32 v218, 0x3fff, v97
	v_lshl_add_u32 v218, v218, 7, v202
	global_load_dwordx4 v[8:11], v218, s[42:43]
	v_bfe_u32 v218, v97, 16, 14
	v_lshl_add_u32 v218, v218, 7, v202
	global_load_dwordx4 v[12:15], v218, s[42:43]
	v_and_b32_e32 v218, 0x3fff, v98
	v_lshl_add_u32 v218, v218, 7, v202
	global_load_dwordx4 v[16:19], v218, s[42:43]
	v_bfe_u32 v218, v98, 16, 14
	v_lshl_add_u32 v218, v218, 7, v202
	global_load_dwordx4 v[20:23], v218, s[42:43]
	v_and_b32_e32 v218, 0x3fff, v99
	v_lshl_add_u32 v218, v218, 7, v202
	global_load_dwordx4 v[24:27], v218, s[42:43]
	v_bfe_u32 v218, v99, 16, 14
	v_lshl_add_u32 v218, v218, 7, v202
	global_load_dwordx4 v[28:31], v218, s[42:43]
	v_and_b32_e32 v218, 0x3fff, v100
	v_lshl_add_u32 v218, v218, 7, v202
	global_load_dwordx4 v[32:35], v218, s[42:43]
	v_bfe_u32 v218, v100, 16, 14
	v_lshl_add_u32 v218, v218, 7, v202
	global_load_dwordx4 v[36:39], v218, s[42:43]
	v_and_b32_e32 v218, 0x3fff, v101
	v_lshl_add_u32 v218, v218, 7, v202
	global_load_dwordx4 v[40:43], v218, s[42:43]
	v_bfe_u32 v218, v101, 16, 14
	v_lshl_add_u32 v218, v218, 7, v202
	global_load_dwordx4 v[44:47], v218, s[42:43]
	v_and_b32_e32 v218, 0x3fff, v102
	v_lshl_add_u32 v218, v218, 7, v202
	global_load_dwordx4 v[48:51], v218, s[42:43]
	v_bfe_u32 v218, v102, 16, 14
	v_lshl_add_u32 v218, v218, 7, v202
	global_load_dwordx4 v[52:55], v218, s[42:43]
	v_and_b32_e32 v218, 0x3fff, v103
	v_lshl_add_u32 v218, v218, 7, v202
	global_load_dwordx4 v[56:59], v218, s[42:43]
	v_bfe_u32 v218, v103, 16, 14
	v_lshl_add_u32 v218, v218, 7, v202
	global_load_dwordx4 v[60:63], v218, s[42:43]
	v_and_b32_e32 v218, 0x3fff, v104
	v_lshl_add_u32 v218, v218, 7, v202
	global_load_dwordx4 v[64:67], v218, s[42:43]
	v_bfe_u32 v218, v104, 16, 14
	v_lshl_add_u32 v218, v218, 7, v202
	global_load_dwordx4 v[68:71], v218, s[42:43]
	v_and_b32_e32 v218, 0x3fff, v105
	v_lshl_add_u32 v218, v218, 7, v202
	global_load_dwordx4 v[72:75], v218, s[42:43]
	v_bfe_u32 v218, v105, 16, 14
	v_lshl_add_u32 v218, v218, 7, v202
	global_load_dwordx4 v[76:79], v218, s[42:43]
	v_and_b32_e32 v218, 0x3fff, v106
	v_lshl_add_u32 v218, v218, 7, v202
	global_load_dwordx4 v[80:83], v218, s[42:43]
	v_bfe_u32 v218, v106, 16, 14
	v_lshl_add_u32 v218, v218, 7, v202
	global_load_dwordx4 v[84:87], v218, s[42:43]
	v_and_b32_e32 v218, 0x3fff, v107
	v_lshl_add_u32 v218, v218, 7, v202
	global_load_dwordx4 v[88:91], v218, s[42:43]
	v_bfe_u32 v218, v107, 16, 14
	v_lshl_add_u32 v218, v218, 7, v202
	global_load_dwordx4 v[92:95], v218, s[42:43]
	v_and_b32_e32 v112, 0x3fff, v108
	v_lshl_add_u32 v112, v112, 7, v202
	v_bfe_u32 v113, v108, 16, 14
	v_lshl_add_u32 v113, v113, 7, v202
	v_and_b32_e32 v114, 0x3fff, v109
	v_lshl_add_u32 v114, v114, 7, v202
	v_bfe_u32 v115, v109, 16, 14
	v_lshl_add_u32 v115, v115, 7, v202
	v_and_b32_e32 v116, 0x3fff, v110
	v_lshl_add_u32 v116, v116, 7, v202
	v_bfe_u32 v117, v110, 16, 14
	v_lshl_add_u32 v117, v117, 7, v202
	v_and_b32_e32 v118, 0x3fff, v111
	v_lshl_add_u32 v118, v118, 7, v202
	v_bfe_u32 v119, v111, 16, 14
	v_lshl_add_u32 v119, v119, 7, v202
	v_lshrrev_b32_e32 v136, v227, v220
	v_lshrrev_b32_e32 v137, v227, v221
	v_lshrrev_b32_e32 v138, v227, v222
	v_lshrrev_b32_e32 v139, v227, v223
	v_and_b32_e32 v136, 0x3fff, v136
	v_and_b32_e32 v137, 0x3fff, v137
	v_and_b32_e32 v138, 0x3fff, v138
	v_and_b32_e32 v139, 0x3fff, v139
	v_lshlrev_b32_e32 v136, 7, v136
	v_lshlrev_b32_e32 v137, 7, v137
	v_lshlrev_b32_e32 v138, 7, v138
	v_lshlrev_b32_e32 v139, 7, v139
	ds_write_b128 v213, v[136:139] offset:1152
	v_lshlrev_b32_e32 v218, 16, v230
	v_and_b32_e32 v219, 0xffff0000, v230
	v_lshlrev_b32_e32 v246, 16, v231
	v_and_b32_e32 v247, 0xffff0000, v231
	v_cvt_pk_fp8_f32 v128, v218, v219
	s_nop 0
	v_cvt_pk_fp8_f32 v128, v246, v247 op_sel:[0,0,1]
	v_lshlrev_b32_e32 v218, 16, v232
	v_and_b32_e32 v219, 0xffff0000, v232
	v_lshlrev_b32_e32 v246, 16, v233
	v_and_b32_e32 v247, 0xffff0000, v233
	v_cvt_pk_fp8_f32 v129, v218, v219
	s_nop 0
	v_cvt_pk_fp8_f32 v129, v246, v247 op_sel:[0,0,1]
	v_lshlrev_b32_e32 v218, 16, v234
	v_and_b32_e32 v219, 0xffff0000, v234
	v_lshlrev_b32_e32 v246, 16, v235
	v_and_b32_e32 v247, 0xffff0000, v235
	v_cvt_pk_fp8_f32 v130, v218, v219
	s_nop 0
	v_cvt_pk_fp8_f32 v130, v246, v247 op_sel:[0,0,1]
	v_lshlrev_b32_e32 v218, 16, v236
	v_and_b32_e32 v219, 0xffff0000, v236
	v_lshlrev_b32_e32 v246, 16, v237
	v_and_b32_e32 v247, 0xffff0000, v237
	v_cvt_pk_fp8_f32 v131, v218, v219
	s_nop 0
	v_cvt_pk_fp8_f32 v131, v246, v247 op_sel:[0,0,1]
	v_lshlrev_b32_e32 v218, 16, v238
	v_and_b32_e32 v219, 0xffff0000, v238
	v_lshlrev_b32_e32 v246, 16, v239
	v_and_b32_e32 v247, 0xffff0000, v239
	v_cvt_pk_fp8_f32 v132, v218, v219
	s_nop 0
	v_cvt_pk_fp8_f32 v132, v246, v247 op_sel:[0,0,1]
	v_lshlrev_b32_e32 v218, 16, v240
	v_and_b32_e32 v219, 0xffff0000, v240
	v_lshlrev_b32_e32 v246, 16, v241
	v_and_b32_e32 v247, 0xffff0000, v241
	v_cvt_pk_fp8_f32 v133, v218, v219
	s_nop 0
	v_cvt_pk_fp8_f32 v133, v246, v247 op_sel:[0,0,1]
	v_lshlrev_b32_e32 v218, 16, v242
	v_and_b32_e32 v219, 0xffff0000, v242
	v_lshlrev_b32_e32 v246, 16, v243
	v_and_b32_e32 v247, 0xffff0000, v243
	v_cvt_pk_fp8_f32 v134, v218, v219
	s_nop 0
	v_cvt_pk_fp8_f32 v134, v246, v247 op_sel:[0,0,1]
	v_lshlrev_b32_e32 v218, 16, v244
	v_and_b32_e32 v219, 0xffff0000, v244
	v_lshlrev_b32_e32 v246, 16, v245
	v_and_b32_e32 v247, 0xffff0000, v245
	v_cvt_pk_fp8_f32 v135, v218, v219
	s_nop 0
	v_cvt_pk_fp8_f32 v135, v246, v247 op_sel:[0,0,1]
	s_add_i32 s49, s34, s48
	s_min_i32 s49, s49, 0x3fff
	s_lshl_b32 s0, s49, 9
	s_add_u32 s0, s38, s0
	s_addc_u32 s1, s39, 0
	s_mul_i32 s4, s49, 0x3c00
	s_add_u32 s4, s40, s4
	s_addc_u32 s5, s41, 0
	global_load_dwordx4 v[96:99], v200, s[0:1]
	global_load_dwordx4 v[100:103], v200, s[0:1] offset:16
	global_load_dwordx4 v[104:107], v200, s[0:1] offset:32
	global_load_dwordx4 v[108:111], v200, s[0:1] offset:48
	global_load_dwordx4 v[220:223], v216, s[0:1]
	global_load_dwordx4 v[230:233], v201, s[4:5]
	global_load_dwordx4 v[234:237], v201, s[4:5] offset:16
	global_load_dwordx4 v[238:241], v201, s[4:5] offset:128
	global_load_dwordx4 v[242:245], v201, s[4:5] offset:144
	s_waitcnt vmcnt(31)
; __device__ __forceinline__ void sparse_unit7(const bf16_t* QKV, const unsigned char* K8, const unsigned char* V8, const int (&selv)[4], bf16_t* OB, LAS unsigned char* wl, int t, int h, int lane) {
;     ...
;             f32x4 acc[4];
; #pragma unroll
;             for (int g = 0; g < 4; ++g) { acc[g] = (f32x4){0.f, 0.f, 0.f, 0.f};
; #pragma unroll
;                 for (int ks = 0; ks < 4; ++ks) acc[g] = __builtin_amdgcn_mfma_f32_16x16x32_fp8_fp8(qa[ks], kf[g * 4 + ks], acc[g], 0, 0, 0); }
;             float sc = (slab == 0) ? acc[0][0] : (slab == 1) ? acc[1][0] : (slab == 2) ? acc[2][0] : acc[3][0];
	ds_write_b128 v224, v[0:3] offset:0
	ds_write_b128 v224, v[4:7] offset:1024
	ds_read_b128 v[144:147], v225 offset:0
	ds_read_b128 v[148:151], v226 offset:0
	global_load_dwordx4 v[0:3], v112, s[42:43]
	global_load_dwordx4 v[4:7], v113, s[42:43]
	s_waitcnt vmcnt(31)
	ds_write_b128 v224, v[8:11] offset:2048
	ds_write_b128 v224, v[12:15] offset:3072
	ds_read_b128 v[152:155], v225 offset:2048
	ds_read_b128 v[156:159], v226 offset:2048
	global_load_dwordx4 v[8:11], v114, s[42:43]
	global_load_dwordx4 v[12:15], v115, s[42:43]
	s_waitcnt lgkmcnt(4)
	v_mfma_f32_16x16x32_fp8_fp8 v[184:187], v[128:129], v[144:145], 0
	v_mfma_f32_16x16x32_fp8_fp8 v[184:187], v[130:131], v[146:147], v[184:187]
	v_mfma_f32_16x16x32_fp8_fp8 v[184:187], v[132:133], v[148:149], v[184:187]
	v_mfma_f32_16x16x32_fp8_fp8 v[184:187], v[134:135], v[150:151], v[184:187]
	s_waitcnt vmcnt(31)
	ds_write_b128 v224, v[16:19] offset:0
	ds_write_b128 v224, v[20:23] offset:1024
	ds_read_b128 v[144:147], v225 offset:0
	ds_read_b128 v[148:151], v226 offset:0
	global_load_dwordx4 v[16:19], v116, s[42:43]
	global_load_dwordx4 v[20:23], v117, s[42:43]
	s_waitcnt lgkmcnt(4)
	v_mfma_f32_16x16x32_fp8_fp8 v[188:191], v[128:129], v[152:153], 0
	v_mfma_f32_16x16x32_fp8_fp8 v[188:191], v[130:131], v[154:155], v[188:191]
	v_mfma_f32_16x16x32_fp8_fp8 v[188:191], v[132:133], v[156:157], v[188:191]
	v_mfma_f32_16x16x32_fp8_fp8 v[188:191], v[134:135], v[158:159], v[188:191]
	s_waitcnt vmcnt(31)
	ds_write_b128 v224, v[24:27] offset:2048
	ds_write_b128 v224, v[28:31] offset:3072
	ds_read_b128 v[152:155], v225 offset:2048
	ds_read_b128 v[156:159], v226 offset:2048
	global_load_dwordx4 v[24:27], v118, s[42:43]
	global_load_dwordx4 v[28:31], v119, s[42:43]
	s_waitcnt lgkmcnt(4)
	v_mfma_f32_16x16x32_fp8_fp8 v[192:195], v[128:129], v[144:145], 0
	v_mfma_f32_16x16x32_fp8_fp8 v[192:195], v[130:131], v[146:147], v[192:195]
	v_mfma_f32_16x16x32_fp8_fp8 v[192:195], v[132:133], v[148:149], v[192:195]
	v_mfma_f32_16x16x32_fp8_fp8 v[192:195], v[134:135], v[150:151], v[192:195]
	v_cndmask_b32_e64 v140, v140, v184, s[8:9]
	s_waitcnt vmcnt(31)
	ds_write_b128 v224, v[32:35] offset:0
	ds_write_b128 v224, v[36:39] offset:1024
	ds_read_b128 v[144:147], v225 offset:0
	ds_read_b128 v[148:151], v226 offset:0
	s_waitcnt lgkmcnt(4)
	v_mfma_f32_16x16x32_fp8_fp8 v[196:199], v[128:129], v[152:153], 0
	v_mfma_f32_16x16x32_fp8_fp8 v[196:199], v[130:131], v[154:155], v[196:199]
	v_mfma_f32_16x16x32_fp8_fp8 v[196:199], v[132:133], v[156:157], v[196:199]
	v_mfma_f32_16x16x32_fp8_fp8 v[196:199], v[134:135], v[158:159], v[196:199]
	v_cndmask_b32_e64 v141, v141, v188, s[8:9]
	s_waitcnt vmcnt(29)
	ds_write_b128 v224, v[40:43] offset:2048
	ds_write_b128 v224, v[44:47] offset:3072
	ds_read_b128 v[152:155], v225 offset:2048
	ds_read_b128 v[156:159], v226 offset:2048
	s_waitcnt lgkmcnt(4)
	v_mfma_f32_16x16x32_fp8_fp8 v[184:187], v[128:129], v[144:145], 0
	v_mfma_f32_16x16x32_fp8_fp8 v[184:187], v[130:131], v[146:147], v[184:187]
	v_mfma_f32_16x16x32_fp8_fp8 v[184:187], v[132:133], v[148:149], v[184:187]
	v_mfma_f32_16x16x32_fp8_fp8 v[184:187], v[134:135], v[150:151], v[184:187]
	v_cndmask_b32_e64 v142, v142, v192, s[8:9]
	s_waitcnt vmcnt(27)
	ds_write_b128 v224, v[48:51] offset:0
	ds_write_b128 v224, v[52:55] offset:1024
	ds_read_b128 v[144:147], v225 offset:0
	ds_read_b128 v[148:151], v226 offset:0
	s_waitcnt lgkmcnt(4)
	v_mfma_f32_16x16x32_fp8_fp8 v[188:191], v[128:129], v[152:153], 0
	v_mfma_f32_16x16x32_fp8_fp8 v[188:191], v[130:131], v[154:155], v[188:191]
	v_mfma_f32_16x16x32_fp8_fp8 v[188:191], v[132:133], v[156:157], v[188:191]
	v_mfma_f32_16x16x32_fp8_fp8 v[188:191], v[134:135], v[158:159], v[188:191]
	v_cndmask_b32_e64 v143, v143, v196, s[8:9]
	s_waitcnt vmcnt(25)
	ds_write_b128 v224, v[56:59] offset:2048
	ds_write_b128 v224, v[60:63] offset:3072
	ds_read_b128 v[152:155], v225 offset:2048
	ds_read_b128 v[156:159], v226 offset:2048
	s_waitcnt lgkmcnt(4)
	v_mfma_f32_16x16x32_fp8_fp8 v[192:195], v[128:129], v[144:145], 0
	v_mfma_f32_16x16x32_fp8_fp8 v[192:195], v[130:131], v[146:147], v[192:195]
	v_mfma_f32_16x16x32_fp8_fp8 v[192:195], v[132:133], v[148:149], v[192:195]
	v_mfma_f32_16x16x32_fp8_fp8 v[192:195], v[134:135], v[150:151], v[192:195]
	v_cndmask_b32_e64 v140, v140, v184, s[10:11]
	s_waitcnt vmcnt(23)
	ds_write_b128 v224, v[64:67] offset:0
	ds_write_b128 v224, v[68:71] offset:1024
	ds_read_b128 v[144:147], v225 offset:0
	ds_read_b128 v[148:151], v226 offset:0
	s_waitcnt lgkmcnt(4)
	v_mfma_f32_16x16x32_fp8_fp8 v[196:199], v[128:129], v[152:153], 0
	v_mfma_f32_16x16x32_fp8_fp8 v[196:199], v[130:131], v[154:155], v[196:199]
	v_mfma_f32_16x16x32_fp8_fp8 v[196:199], v[132:133], v[156:157], v[196:199]
	v_mfma_f32_16x16x32_fp8_fp8 v[196:199], v[134:135], v[158:159], v[196:199]
	v_cndmask_b32_e64 v141, v141, v188, s[10:11]
	s_waitcnt vmcnt(21)
	ds_write_b128 v224, v[72:75] offset:2048
	ds_write_b128 v224, v[76:79] offset:3072
	ds_read_b128 v[152:155], v225 offset:2048
	ds_read_b128 v[156:159], v226 offset:2048
	s_waitcnt lgkmcnt(4)
	v_mfma_f32_16x16x32_fp8_fp8 v[184:187], v[128:129], v[144:145], 0
	v_mfma_f32_16x16x32_fp8_fp8 v[184:187], v[130:131], v[146:147], v[184:187]
	v_mfma_f32_16x16x32_fp8_fp8 v[184:187], v[132:133], v[148:149], v[184:187]
	v_mfma_f32_16x16x32_fp8_fp8 v[184:187], v[134:135], v[150:151], v[184:187]
	v_cndmask_b32_e64 v142, v142, v192, s[10:11]
	s_waitcnt vmcnt(19)
	ds_write_b128 v224, v[80:83] offset:0
	ds_write_b128 v224, v[84:87] offset:1024
	ds_read_b128 v[144:147], v225 offset:0
	ds_read_b128 v[148:151], v226 offset:0
	s_waitcnt lgkmcnt(4)
; __device__ __forceinline__ void sparse_unit7(const bf16_t* QKV, const unsigned char* K8, const unsigned char* V8, const int (&selv)[4], bf16_t* OB, LAS unsigned char* wl, int t, int h, int lane) {
;     ...
;             s9_issue_v<1>(vb, V8h, ot, half, l4);
;             f32x4 acc[4];
; #pragma unroll
;             for (int g = 0; g < 4; ++g) { acc[g] = (f32x4){0.f, 0.f, 0.f, 0.f};
; #pragma unroll
;                 for (int ks = 0; ks < 4; ++ks) acc[g] = __builtin_amdgcn_mfma_f32_16x16x32_fp8_fp8(qa[ks], kf[g * 4 + ks], acc[g], 0, 0, 0); }
;             float sc = (slab == 0) ? acc[0][0] : (slab == 1) ? acc[1][0] : (slab == 2) ? acc[2][0] : acc[3][0];
;             sc = valid ? sc * 0.08838834764831845f : -INFINITY;
;             const float mn = fmaxf(m, wave_max(sc));
	v_mfma_f32_16x16x32_fp8_fp8 v[188:191], v[128:129], v[152:153], 0
	v_mfma_f32_16x16x32_fp8_fp8 v[188:191], v[130:131], v[154:155], v[188:191]
	v_mfma_f32_16x16x32_fp8_fp8 v[188:191], v[132:133], v[156:157], v[188:191]
	v_mfma_f32_16x16x32_fp8_fp8 v[188:191], v[134:135], v[158:159], v[188:191]
	v_cndmask_b32_e64 v143, v143, v196, s[10:11]
	s_waitcnt vmcnt(17)
	ds_write_b128 v224, v[88:91] offset:2048
	ds_write_b128 v224, v[92:95] offset:3072
	ds_read_b128 v[152:155], v225 offset:2048
	ds_read_b128 v[156:159], v226 offset:2048
	s_waitcnt lgkmcnt(4)
	v_mfma_f32_16x16x32_fp8_fp8 v[192:195], v[128:129], v[144:145], 0
	v_mfma_f32_16x16x32_fp8_fp8 v[192:195], v[130:131], v[146:147], v[192:195]
	v_mfma_f32_16x16x32_fp8_fp8 v[192:195], v[132:133], v[148:149], v[192:195]
	v_mfma_f32_16x16x32_fp8_fp8 v[192:195], v[134:135], v[150:151], v[192:195]
	v_cndmask_b32_e64 v140, v140, v184, s[16:17]
	s_waitcnt vmcnt(6)
	ds_write_b128 v224, v[0:3] offset:0
	ds_write_b128 v224, v[4:7] offset:1024
	ds_read_b128 v[144:147], v225 offset:0
	ds_read_b128 v[148:151], v226 offset:0
	s_waitcnt lgkmcnt(4)
	v_mfma_f32_16x16x32_fp8_fp8 v[196:199], v[128:129], v[152:153], 0
	v_mfma_f32_16x16x32_fp8_fp8 v[196:199], v[130:131], v[154:155], v[196:199]
	v_mfma_f32_16x16x32_fp8_fp8 v[196:199], v[132:133], v[156:157], v[196:199]
	v_mfma_f32_16x16x32_fp8_fp8 v[196:199], v[134:135], v[158:159], v[196:199]
	v_cndmask_b32_e64 v141, v141, v188, s[16:17]
	s_waitcnt vmcnt(4)
	ds_write_b128 v224, v[8:11] offset:2048
	ds_write_b128 v224, v[12:15] offset:3072
	ds_read_b128 v[152:155], v225 offset:2048
	ds_read_b128 v[156:159], v226 offset:2048
	s_waitcnt lgkmcnt(4)
	v_mfma_f32_16x16x32_fp8_fp8 v[184:187], v[128:129], v[144:145], 0
	v_mfma_f32_16x16x32_fp8_fp8 v[184:187], v[130:131], v[146:147], v[184:187]
	v_mfma_f32_16x16x32_fp8_fp8 v[184:187], v[132:133], v[148:149], v[184:187]
	v_mfma_f32_16x16x32_fp8_fp8 v[184:187], v[134:135], v[150:151], v[184:187]
	v_cndmask_b32_e64 v142, v142, v192, s[16:17]
	s_waitcnt vmcnt(2)
	ds_write_b128 v224, v[16:19] offset:0
	ds_write_b128 v224, v[20:23] offset:1024
	ds_read_b128 v[144:147], v225 offset:0
	ds_read_b128 v[148:151], v226 offset:0
	s_waitcnt lgkmcnt(4)
	v_mfma_f32_16x16x32_fp8_fp8 v[188:191], v[128:129], v[152:153], 0
	v_mfma_f32_16x16x32_fp8_fp8 v[188:191], v[130:131], v[154:155], v[188:191]
	v_mfma_f32_16x16x32_fp8_fp8 v[188:191], v[132:133], v[156:157], v[188:191]
	v_mfma_f32_16x16x32_fp8_fp8 v[188:191], v[134:135], v[158:159], v[188:191]
	v_cndmask_b32_e64 v143, v143, v196, s[16:17]
	s_waitcnt vmcnt(0)
	ds_write_b128 v224, v[24:27] offset:2048
	ds_write_b128 v224, v[28:31] offset:3072
	ds_read_b128 v[152:155], v225 offset:2048
	ds_read_b128 v[156:159], v226 offset:2048
	s_waitcnt lgkmcnt(4)
	v_mfma_f32_16x16x32_fp8_fp8 v[192:195], v[128:129], v[144:145], 0
	v_mfma_f32_16x16x32_fp8_fp8 v[192:195], v[130:131], v[146:147], v[192:195]
	v_mfma_f32_16x16x32_fp8_fp8 v[192:195], v[132:133], v[148:149], v[192:195]
	v_mfma_f32_16x16x32_fp8_fp8 v[192:195], v[134:135], v[150:151], v[192:195]
	v_cndmask_b32_e64 v140, v140, v184, s[22:23]
	s_waitcnt lgkmcnt(0)
	v_mfma_f32_16x16x32_fp8_fp8 v[196:199], v[128:129], v[152:153], 0
	v_mfma_f32_16x16x32_fp8_fp8 v[196:199], v[130:131], v[154:155], v[196:199]
	v_mfma_f32_16x16x32_fp8_fp8 v[196:199], v[132:133], v[156:157], v[196:199]
	v_mfma_f32_16x16x32_fp8_fp8 v[196:199], v[134:135], v[158:159], v[196:199]
	ds_read_b128 v[64:67], v214 offset:1152
	ds_read_b128 v[68:71], v214 offset:1168
	ds_read_b128 v[72:75], v214 offset:1184
	ds_read_b128 v[76:79], v214 offset:1200
	ds_read_b128 v[80:83], v214 offset:1216
	ds_read_b128 v[84:87], v214 offset:1232
	ds_read_b128 v[88:91], v214 offset:1248
	ds_read_b128 v[92:95], v214 offset:1264
	s_waitcnt lgkmcnt(0)
	v_or_b32_e32 v218, v64, v203
	global_load_dwordx4 v[0:3], v218, s[44:45]
	v_or_b32_e32 v218, v65, v203
	global_load_dwordx4 v[4:7], v218, s[44:45]
	v_or_b32_e32 v218, v66, v203
	global_load_dwordx4 v[8:11], v218, s[44:45]
	v_or_b32_e32 v218, v67, v203
	global_load_dwordx4 v[12:15], v218, s[44:45]
	v_or_b32_e32 v218, v68, v203
	global_load_dwordx4 v[16:19], v218, s[44:45]
	v_or_b32_e32 v218, v69, v203
	global_load_dwordx4 v[20:23], v218, s[44:45]
	v_or_b32_e32 v218, v70, v203
	global_load_dwordx4 v[24:27], v218, s[44:45]
	v_or_b32_e32 v218, v71, v203
	global_load_dwordx4 v[28:31], v218, s[44:45]
	v_or_b32_e32 v218, v72, v203
	global_load_dwordx4 v[32:35], v218, s[44:45]
	v_or_b32_e32 v218, v73, v203
	global_load_dwordx4 v[36:39], v218, s[44:45]
	v_or_b32_e32 v218, v74, v203
	global_load_dwordx4 v[40:43], v218, s[44:45]
	v_or_b32_e32 v218, v75, v203
	global_load_dwordx4 v[44:47], v218, s[44:45]
	v_or_b32_e32 v218, v76, v203
	global_load_dwordx4 v[48:51], v218, s[44:45]
	v_or_b32_e32 v218, v77, v203
	global_load_dwordx4 v[52:55], v218, s[44:45]
	v_or_b32_e32 v218, v78, v203
	global_load_dwordx4 v[56:59], v218, s[44:45]
	v_or_b32_e32 v218, v79, v203
	global_load_dwordx4 v[60:63], v218, s[44:45]
	v_cndmask_b32_e64 v141, v141, v188, s[22:23]
	s_nop 7
	v_cndmask_b32_e64 v142, v142, v192, s[22:23]
	s_nop 7
	v_cndmask_b32_e64 v143, v143, v196, s[22:23]
	s_sub_i32 s99, s98, 0
	v_mul_f32_e32 v140, 0x3db504f3, v140
	v_cmp_gt_i32_e32 vcc, s99, v217
	s_nop 1
	v_cndmask_b32_e32 v140, v208, v140, vcc
	s_sub_i32 s99, s98, 2
	v_mul_f32_e32 v141, 0x3db504f3, v141
	v_cmp_gt_i32_e32 vcc, s99, v217
	s_nop 1
	v_cndmask_b32_e32 v141, v208, v141, vcc
	s_sub_i32 s99, s98, 4
	v_mul_f32_e32 v142, 0x3db504f3, v142
	v_cmp_gt_i32_e32 vcc, s99, v217
	s_nop 1
	v_cndmask_b32_e32 v142, v208, v142, vcc
	s_sub_i32 s99, s98, 6
	v_mul_f32_e32 v143, 0x3db504f3, v143
	v_cmp_gt_i32_e32 vcc, s99, v217
; #define LAS __attribute__((address_space(3)))
; template <int Q> __device__ __forceinline__ void s9_pv(const unsigned (&vv)[8], LAS const float* ptw, int half, f32x2_t& oa, f32x2_t& ob) {
; #pragma unroll
;     for (int u2 = 0; u2 < 8; ++u2) { const float p = ptw[2 * (Q * 8 + u2) + half];
;         oa = __builtin_amdgcn_cvt_pk_f32_fp8((int)vv[u2], false) * p + oa; ob = __builtin_amdgcn_cvt_pk_f32_fp8((int)vv[u2], true) * p + ob; }
; }
; __device__ __forceinline__ void sparse_unit7(const bf16_t* QKV, const unsigned char* K8, const unsigned char* V8, const int (&selv)[4], bf16_t* OB, LAS unsigned char* wl, int t, int h, int lane) {
;     ...
;             sc = valid ? sc * 0.08838834764831845f : -INFINITY;
;             const float mn = fmaxf(m, wave_max(sc));
;             const float alpha = __expf(m - mn), p = __expf(sc - mn);
;             oa = oa * alpha; ob = ob * alpha; m = mn; l = l * alpha + p;
;             pt[lane] = p;
;             asm volatile("" ::: "memory");
;             const int sn_ = (s < 3) ? (s + 1) : 3;
;             s8_issue_k(kf, K8h, wsel, 64 * sn_, n16, slab);
;             s9_pv<0>(va, pt, half, oa, ob);
	s_nop 1
	v_cndmask_b32_e32 v143, v208, v143, vcc
	v_max_f32_e32 v218, v140, v141
	v_max3_f32 v218, v218, v142, v143
	s_nop 1
	v_max_f32_dpp v218, v218, v218 row_ror:8 row_mask:0xf bank_mask:0xf bound_ctrl:1
	s_nop 1
	v_max_f32_dpp v218, v218, v218 row_ror:4 row_mask:0xf bank_mask:0xf bound_ctrl:1
	s_nop 1
	v_max_f32_dpp v218, v218, v218 quad_perm:[2,3,0,1] row_mask:0xf bank_mask:0xf bound_ctrl:1
	s_nop 1
	v_max_f32_dpp v218, v218, v218 quad_perm:[1,0,3,2] row_mask:0xf bank_mask:0xf bound_ctrl:1
	v_mov_b32_e32 v219, v218
	s_nop 1
	v_permlane16_swap_b32_e32 v218, v219
	s_nop 1
	v_max_f32_e32 v218, v218, v219
	v_mov_b32_e32 v219, v218
	s_nop 1
	v_permlane32_swap_b32_e32 v218, v219
	s_nop 1
	v_max_f32_e32 v218, v218, v219
	v_sub_f32_e32 v140, v140, v218
	v_sub_f32_e32 v141, v141, v218
	v_sub_f32_e32 v142, v142, v218
	v_sub_f32_e32 v143, v143, v218
	v_mul_f32_e32 v140, 0x3fb8aa3b, v140
	v_mul_f32_e32 v141, 0x3fb8aa3b, v141
	v_mul_f32_e32 v142, 0x3fb8aa3b, v142
	v_mul_f32_e32 v143, 0x3fb8aa3b, v143
	v_exp_f32_e32 v140, v140
	v_exp_f32_e32 v141, v141
	v_exp_f32_e32 v142, v142
	v_exp_f32_e32 v143, v143
	s_nop 1
	ds_write_b128 v213, v[140:143]
	v_add_f32_e32 v246, v140, v141
	v_add_f32_e32 v247, v142, v143
	v_add_f32_e32 v246, v246, v247
	ds_read_b128 v[112:115], v214 offset:0
	ds_read_b128 v[116:119], v214 offset:16
	ds_read_b128 v[120:123], v214 offset:32
	ds_read_b128 v[124:127], v214 offset:48
	v_mov_b32_e32 v144, 0
	v_mov_b32_e32 v145, 0
	v_mov_b32_e32 v146, 0
	v_mov_b32_e32 v147, 0
	v_mov_b32_e32 v148, 0
	v_mov_b32_e32 v149, 0
	v_mov_b32_e32 v150, 0
	v_mov_b32_e32 v151, 0
	v_mov_b32_e32 v152, 0
	v_mov_b32_e32 v153, 0
	v_mov_b32_e32 v154, 0
	v_mov_b32_e32 v155, 0
	v_mov_b32_e32 v156, 0
	v_mov_b32_e32 v157, 0
	v_mov_b32_e32 v158, 0
	v_mov_b32_e32 v159, 0
	s_nop 1
	v_add_f32_dpp v246, v246, v246 row_ror:8 row_mask:0xf bank_mask:0xf bound_ctrl:1
	s_nop 1
	v_add_f32_dpp v246, v246, v246 row_ror:4 row_mask:0xf bank_mask:0xf bound_ctrl:1
	s_nop 1
	v_add_f32_dpp v246, v246, v246 quad_perm:[2,3,0,1] row_mask:0xf bank_mask:0xf bound_ctrl:1
	s_nop 1
	v_add_f32_dpp v246, v246, v246 quad_perm:[1,0,3,2] row_mask:0xf bank_mask:0xf bound_ctrl:1
	v_mov_b32_e32 v247, v246
	s_nop 1
	v_permlane16_swap_b32_e32 v246, v247
	s_nop 1
	v_add_f32_e32 v246, v246, v247
	v_mov_b32_e32 v247, v246
	s_nop 1
	v_permlane32_swap_b32_e32 v246, v247
	s_nop 1
	v_add_f32_e32 v246, v246, v247
	s_waitcnt lgkmcnt(0)
	s_waitcnt vmcnt(15)
	v_cvt_pk_f32_fp8_e32 v[184:185], v0
	v_cvt_pk_f32_fp8_sdwa v[186:187], v0 src0_sel:WORD_1
	v_cvt_pk_f32_fp8_e32 v[188:189], v1
	v_cvt_pk_f32_fp8_sdwa v[190:191], v1 src0_sel:WORD_1
	v_cvt_pk_f32_fp8_e32 v[192:193], v2
	v_cvt_pk_f32_fp8_sdwa v[194:195], v2 src0_sel:WORD_1
	v_cvt_pk_f32_fp8_e32 v[196:197], v3
	v_cvt_pk_f32_fp8_sdwa v[198:199], v3 src0_sel:WORD_1
	v_or_b32_e32 v218, v80, v203
	global_load_dwordx4 v[0:3], v218, s[44:45]
	v_pk_fma_f32 v[144:145], v[184:185], v[112:113], v[144:145] op_sel_hi:[1,0,1]
	v_pk_fma_f32 v[146:147], v[186:187], v[112:113], v[146:147] op_sel_hi:[1,0,1]
	v_pk_fma_f32 v[148:149], v[188:189], v[112:113], v[148:149] op_sel_hi:[1,0,1]
	v_pk_fma_f32 v[150:151], v[190:191], v[112:113], v[150:151] op_sel_hi:[1,0,1]
	v_pk_fma_f32 v[152:153], v[192:193], v[112:113], v[152:153] op_sel_hi:[1,0,1]
	v_pk_fma_f32 v[154:155], v[194:195], v[112:113], v[154:155] op_sel_hi:[1,0,1]
	v_pk_fma_f32 v[156:157], v[196:197], v[112:113], v[156:157] op_sel_hi:[1,0,1]
	v_pk_fma_f32 v[158:159], v[198:199], v[112:113], v[158:159] op_sel_hi:[1,0,1]
	s_waitcnt vmcnt(15)
	v_cvt_pk_f32_fp8_e32 v[184:185], v4
	v_cvt_pk_f32_fp8_sdwa v[186:187], v4 src0_sel:WORD_1
	v_cvt_pk_f32_fp8_e32 v[188:189], v5
	v_cvt_pk_f32_fp8_sdwa v[190:191], v5 src0_sel:WORD_1
	v_cvt_pk_f32_fp8_e32 v[192:193], v6
	v_cvt_pk_f32_fp8_sdwa v[194:195], v6 src0_sel:WORD_1
	v_cvt_pk_f32_fp8_e32 v[196:197], v7
	v_cvt_pk_f32_fp8_sdwa v[198:199], v7 src0_sel:WORD_1
	v_or_b32_e32 v218, v81, v203
	global_load_dwordx4 v[4:7], v218, s[44:45]
	v_pk_fma_f32 v[144:145], v[184:185], v[112:113], v[144:145] op_sel:[0,1,0] op_sel_hi:[1,1,1]
	v_pk_fma_f32 v[146:147], v[186:187], v[112:113], v[146:147] op_sel:[0,1,0] op_sel_hi:[1,1,1]
	v_pk_fma_f32 v[148:149], v[188:189], v[112:113], v[148:149] op_sel:[0,1,0] op_sel_hi:[1,1,1]
	v_pk_fma_f32 v[150:151], v[190:191], v[112:113], v[150:151] op_sel:[0,1,0] op_sel_hi:[1,1,1]
	v_pk_fma_f32 v[152:153], v[192:193], v[112:113], v[152:153] op_sel:[0,1,0] op_sel_hi:[1,1,1]
	v_pk_fma_f32 v[154:155], v[194:195], v[112:113], v[154:155] op_sel:[0,1,0] op_sel_hi:[1,1,1]
	v_pk_fma_f32 v[156:157], v[196:197], v[112:113], v[156:157] op_sel:[0,1,0] op_sel_hi:[1,1,1]
	v_pk_fma_f32 v[158:159], v[198:199], v[112:113], v[158:159] op_sel:[0,1,0] op_sel_hi:[1,1,1]
	s_waitcnt vmcnt(15)
	v_cvt_pk_f32_fp8_e32 v[184:185], v8
	v_cvt_pk_f32_fp8_sdwa v[186:187], v8 src0_sel:WORD_1
	v_cvt_pk_f32_fp8_e32 v[188:189], v9
	v_cvt_pk_f32_fp8_sdwa v[190:191], v9 src0_sel:WORD_1
	v_cvt_pk_f32_fp8_e32 v[192:193], v10
	v_cvt_pk_f32_fp8_sdwa v[194:195], v10 src0_sel:WORD_1
	v_cvt_pk_f32_fp8_e32 v[196:197], v11
	v_cvt_pk_f32_fp8_sdwa v[198:199], v11 src0_sel:WORD_1
	v_or_b32_e32 v218, v82, v203
	global_load_dwordx4 v[8:11], v218, s[44:45]
	v_pk_fma_f32 v[144:145], v[184:185], v[114:115], v[144:145] op_sel_hi:[1,0,1]
	v_pk_fma_f32 v[146:147], v[186:187], v[114:115], v[146:147] op_sel_hi:[1,0,1]
	v_pk_fma_f32 v[148:149], v[188:189], v[114:115], v[148:149] op_sel_hi:[1,0,1]
	v_pk_fma_f32 v[150:151], v[190:191], v[114:115], v[150:151] op_sel_hi:[1,0,1]
	v_pk_fma_f32 v[152:153], v[192:193], v[114:115], v[152:153] op_sel_hi:[1,0,1]
	v_pk_fma_f32 v[154:155], v[194:195], v[114:115], v[154:155] op_sel_hi:[1,0,1]
	v_pk_fma_f32 v[156:157], v[196:197], v[114:115], v[156:157] op_sel_hi:[1,0,1]
	v_pk_fma_f32 v[158:159], v[198:199], v[114:115], v[158:159] op_sel_hi:[1,0,1]
	s_waitcnt vmcnt(15)
; #define LAS __attribute__((address_space(3)))
; template <int Q> __device__ __forceinline__ void s9_pv(const unsigned (&vv)[8], LAS const float* ptw, int half, f32x2_t& oa, f32x2_t& ob) {
; #pragma unroll
;     for (int u2 = 0; u2 < 8; ++u2) { const float p = ptw[2 * (Q * 8 + u2) + half];
;         oa = __builtin_amdgcn_cvt_pk_f32_fp8((int)vv[u2], false) * p + oa; ob = __builtin_amdgcn_cvt_pk_f32_fp8((int)vv[u2], true) * p + ob; }
; }
	v_cvt_pk_f32_fp8_e32 v[184:185], v12
	v_cvt_pk_f32_fp8_sdwa v[186:187], v12 src0_sel:WORD_1
	v_cvt_pk_f32_fp8_e32 v[188:189], v13
	v_cvt_pk_f32_fp8_sdwa v[190:191], v13 src0_sel:WORD_1
	v_cvt_pk_f32_fp8_e32 v[192:193], v14
	v_cvt_pk_f32_fp8_sdwa v[194:195], v14 src0_sel:WORD_1
	v_cvt_pk_f32_fp8_e32 v[196:197], v15
	v_cvt_pk_f32_fp8_sdwa v[198:199], v15 src0_sel:WORD_1
	v_or_b32_e32 v218, v83, v203
	global_load_dwordx4 v[12:15], v218, s[44:45]
	v_pk_fma_f32 v[144:145], v[184:185], v[114:115], v[144:145] op_sel:[0,1,0] op_sel_hi:[1,1,1]
	v_pk_fma_f32 v[146:147], v[186:187], v[114:115], v[146:147] op_sel:[0,1,0] op_sel_hi:[1,1,1]
	v_pk_fma_f32 v[148:149], v[188:189], v[114:115], v[148:149] op_sel:[0,1,0] op_sel_hi:[1,1,1]
	v_pk_fma_f32 v[150:151], v[190:191], v[114:115], v[150:151] op_sel:[0,1,0] op_sel_hi:[1,1,1]
	v_pk_fma_f32 v[152:153], v[192:193], v[114:115], v[152:153] op_sel:[0,1,0] op_sel_hi:[1,1,1]
	v_pk_fma_f32 v[154:155], v[194:195], v[114:115], v[154:155] op_sel:[0,1,0] op_sel_hi:[1,1,1]
	v_pk_fma_f32 v[156:157], v[196:197], v[114:115], v[156:157] op_sel:[0,1,0] op_sel_hi:[1,1,1]
	v_pk_fma_f32 v[158:159], v[198:199], v[114:115], v[158:159] op_sel:[0,1,0] op_sel_hi:[1,1,1]
	s_waitcnt vmcnt(15)
	v_cvt_pk_f32_fp8_e32 v[184:185], v16
	v_cvt_pk_f32_fp8_sdwa v[186:187], v16 src0_sel:WORD_1
	v_cvt_pk_f32_fp8_e32 v[188:189], v17
	v_cvt_pk_f32_fp8_sdwa v[190:191], v17 src0_sel:WORD_1
	v_cvt_pk_f32_fp8_e32 v[192:193], v18
	v_cvt_pk_f32_fp8_sdwa v[194:195], v18 src0_sel:WORD_1
	v_cvt_pk_f32_fp8_e32 v[196:197], v19
	v_cvt_pk_f32_fp8_sdwa v[198:199], v19 src0_sel:WORD_1
	v_or_b32_e32 v218, v84, v203
	global_load_dwordx4 v[16:19], v218, s[44:45]
	v_pk_fma_f32 v[144:145], v[184:185], v[116:117], v[144:145] op_sel_hi:[1,0,1]
	v_pk_fma_f32 v[146:147], v[186:187], v[116:117], v[146:147] op_sel_hi:[1,0,1]
	v_pk_fma_f32 v[148:149], v[188:189], v[116:117], v[148:149] op_sel_hi:[1,0,1]
	v_pk_fma_f32 v[150:151], v[190:191], v[116:117], v[150:151] op_sel_hi:[1,0,1]
	v_pk_fma_f32 v[152:153], v[192:193], v[116:117], v[152:153] op_sel_hi:[1,0,1]
	v_pk_fma_f32 v[154:155], v[194:195], v[116:117], v[154:155] op_sel_hi:[1,0,1]
	v_pk_fma_f32 v[156:157], v[196:197], v[116:117], v[156:157] op_sel_hi:[1,0,1]
	v_pk_fma_f32 v[158:159], v[198:199], v[116:117], v[158:159] op_sel_hi:[1,0,1]
	s_waitcnt vmcnt(15)
	v_cvt_pk_f32_fp8_e32 v[184:185], v20
	v_cvt_pk_f32_fp8_sdwa v[186:187], v20 src0_sel:WORD_1
	v_cvt_pk_f32_fp8_e32 v[188:189], v21
	v_cvt_pk_f32_fp8_sdwa v[190:191], v21 src0_sel:WORD_1
	v_cvt_pk_f32_fp8_e32 v[192:193], v22
	v_cvt_pk_f32_fp8_sdwa v[194:195], v22 src0_sel:WORD_1
	v_cvt_pk_f32_fp8_e32 v[196:197], v23
	v_cvt_pk_f32_fp8_sdwa v[198:199], v23 src0_sel:WORD_1
	v_or_b32_e32 v218, v85, v203
	global_load_dwordx4 v[20:23], v218, s[44:45]
	v_pk_fma_f32 v[144:145], v[184:185], v[116:117], v[144:145] op_sel:[0,1,0] op_sel_hi:[1,1,1]
	v_pk_fma_f32 v[146:147], v[186:187], v[116:117], v[146:147] op_sel:[0,1,0] op_sel_hi:[1,1,1]
	v_pk_fma_f32 v[148:149], v[188:189], v[116:117], v[148:149] op_sel:[0,1,0] op_sel_hi:[1,1,1]
	v_pk_fma_f32 v[150:151], v[190:191], v[116:117], v[150:151] op_sel:[0,1,0] op_sel_hi:[1,1,1]
	v_pk_fma_f32 v[152:153], v[192:193], v[116:117], v[152:153] op_sel:[0,1,0] op_sel_hi:[1,1,1]
	v_pk_fma_f32 v[154:155], v[194:195], v[116:117], v[154:155] op_sel:[0,1,0] op_sel_hi:[1,1,1]
	v_pk_fma_f32 v[156:157], v[196:197], v[116:117], v[156:157] op_sel:[0,1,0] op_sel_hi:[1,1,1]
	v_pk_fma_f32 v[158:159], v[198:199], v[116:117], v[158:159] op_sel:[0,1,0] op_sel_hi:[1,1,1]
	s_waitcnt vmcnt(15)
	v_cvt_pk_f32_fp8_e32 v[184:185], v24
	v_cvt_pk_f32_fp8_sdwa v[186:187], v24 src0_sel:WORD_1
	v_cvt_pk_f32_fp8_e32 v[188:189], v25
	v_cvt_pk_f32_fp8_sdwa v[190:191], v25 src0_sel:WORD_1
	v_cvt_pk_f32_fp8_e32 v[192:193], v26
	v_cvt_pk_f32_fp8_sdwa v[194:195], v26 src0_sel:WORD_1
	v_cvt_pk_f32_fp8_e32 v[196:197], v27
	v_cvt_pk_f32_fp8_sdwa v[198:199], v27 src0_sel:WORD_1
	v_or_b32_e32 v218, v86, v203
	global_load_dwordx4 v[24:27], v218, s[44:45]
	v_pk_fma_f32 v[144:145], v[184:185], v[118:119], v[144:145] op_sel_hi:[1,0,1]
	v_pk_fma_f32 v[146:147], v[186:187], v[118:119], v[146:147] op_sel_hi:[1,0,1]
	v_pk_fma_f32 v[148:149], v[188:189], v[118:119], v[148:149] op_sel_hi:[1,0,1]
	v_pk_fma_f32 v[150:151], v[190:191], v[118:119], v[150:151] op_sel_hi:[1,0,1]
	v_pk_fma_f32 v[152:153], v[192:193], v[118:119], v[152:153] op_sel_hi:[1,0,1]
	v_pk_fma_f32 v[154:155], v[194:195], v[118:119], v[154:155] op_sel_hi:[1,0,1]
	v_pk_fma_f32 v[156:157], v[196:197], v[118:119], v[156:157] op_sel_hi:[1,0,1]
	v_pk_fma_f32 v[158:159], v[198:199], v[118:119], v[158:159] op_sel_hi:[1,0,1]
	s_waitcnt vmcnt(15)
	v_cvt_pk_f32_fp8_e32 v[184:185], v28
	v_cvt_pk_f32_fp8_sdwa v[186:187], v28 src0_sel:WORD_1
	v_cvt_pk_f32_fp8_e32 v[188:189], v29
	v_cvt_pk_f32_fp8_sdwa v[190:191], v29 src0_sel:WORD_1
	v_cvt_pk_f32_fp8_e32 v[192:193], v30
	v_cvt_pk_f32_fp8_sdwa v[194:195], v30 src0_sel:WORD_1
	v_cvt_pk_f32_fp8_e32 v[196:197], v31
	v_cvt_pk_f32_fp8_sdwa v[198:199], v31 src0_sel:WORD_1
	v_or_b32_e32 v218, v87, v203
	global_load_dwordx4 v[28:31], v218, s[44:45]
	v_pk_fma_f32 v[144:145], v[184:185], v[118:119], v[144:145] op_sel:[0,1,0] op_sel_hi:[1,1,1]
	v_pk_fma_f32 v[146:147], v[186:187], v[118:119], v[146:147] op_sel:[0,1,0] op_sel_hi:[1,1,1]
	v_pk_fma_f32 v[148:149], v[188:189], v[118:119], v[148:149] op_sel:[0,1,0] op_sel_hi:[1,1,1]
	v_pk_fma_f32 v[150:151], v[190:191], v[118:119], v[150:151] op_sel:[0,1,0] op_sel_hi:[1,1,1]
	v_pk_fma_f32 v[152:153], v[192:193], v[118:119], v[152:153] op_sel:[0,1,0] op_sel_hi:[1,1,1]
	v_pk_fma_f32 v[154:155], v[194:195], v[118:119], v[154:155] op_sel:[0,1,0] op_sel_hi:[1,1,1]
	v_pk_fma_f32 v[156:157], v[196:197], v[118:119], v[156:157] op_sel:[0,1,0] op_sel_hi:[1,1,1]
	v_pk_fma_f32 v[158:159], v[198:199], v[118:119], v[158:159] op_sel:[0,1,0] op_sel_hi:[1,1,1]
	s_waitcnt vmcnt(15)
; #define LAS __attribute__((address_space(3)))
; template <int Q> __device__ __forceinline__ void s9_pv(const unsigned (&vv)[8], LAS const float* ptw, int half, f32x2_t& oa, f32x2_t& ob) {
; #pragma unroll
;     for (int u2 = 0; u2 < 8; ++u2) { const float p = ptw[2 * (Q * 8 + u2) + half];
;         oa = __builtin_amdgcn_cvt_pk_f32_fp8((int)vv[u2], false) * p + oa; ob = __builtin_amdgcn_cvt_pk_f32_fp8((int)vv[u2], true) * p + ob; }
; }
	v_cvt_pk_f32_fp8_e32 v[184:185], v32
	v_cvt_pk_f32_fp8_sdwa v[186:187], v32 src0_sel:WORD_1
	v_cvt_pk_f32_fp8_e32 v[188:189], v33
	v_cvt_pk_f32_fp8_sdwa v[190:191], v33 src0_sel:WORD_1
	v_cvt_pk_f32_fp8_e32 v[192:193], v34
	v_cvt_pk_f32_fp8_sdwa v[194:195], v34 src0_sel:WORD_1
	v_cvt_pk_f32_fp8_e32 v[196:197], v35
	v_cvt_pk_f32_fp8_sdwa v[198:199], v35 src0_sel:WORD_1
	v_or_b32_e32 v218, v88, v203
	global_load_dwordx4 v[32:35], v218, s[44:45]
	v_pk_fma_f32 v[144:145], v[184:185], v[120:121], v[144:145] op_sel_hi:[1,0,1]
	v_pk_fma_f32 v[146:147], v[186:187], v[120:121], v[146:147] op_sel_hi:[1,0,1]
	v_pk_fma_f32 v[148:149], v[188:189], v[120:121], v[148:149] op_sel_hi:[1,0,1]
	v_pk_fma_f32 v[150:151], v[190:191], v[120:121], v[150:151] op_sel_hi:[1,0,1]
	v_pk_fma_f32 v[152:153], v[192:193], v[120:121], v[152:153] op_sel_hi:[1,0,1]
	v_pk_fma_f32 v[154:155], v[194:195], v[120:121], v[154:155] op_sel_hi:[1,0,1]
	v_pk_fma_f32 v[156:157], v[196:197], v[120:121], v[156:157] op_sel_hi:[1,0,1]
	v_pk_fma_f32 v[158:159], v[198:199], v[120:121], v[158:159] op_sel_hi:[1,0,1]
	s_waitcnt vmcnt(15)
	v_cvt_pk_f32_fp8_e32 v[184:185], v36
	v_cvt_pk_f32_fp8_sdwa v[186:187], v36 src0_sel:WORD_1
	v_cvt_pk_f32_fp8_e32 v[188:189], v37
	v_cvt_pk_f32_fp8_sdwa v[190:191], v37 src0_sel:WORD_1
	v_cvt_pk_f32_fp8_e32 v[192:193], v38
	v_cvt_pk_f32_fp8_sdwa v[194:195], v38 src0_sel:WORD_1
	v_cvt_pk_f32_fp8_e32 v[196:197], v39
	v_cvt_pk_f32_fp8_sdwa v[198:199], v39 src0_sel:WORD_1
	v_or_b32_e32 v218, v89, v203
	global_load_dwordx4 v[36:39], v218, s[44:45]
	v_pk_fma_f32 v[144:145], v[184:185], v[120:121], v[144:145] op_sel:[0,1,0] op_sel_hi:[1,1,1]
	v_pk_fma_f32 v[146:147], v[186:187], v[120:121], v[146:147] op_sel:[0,1,0] op_sel_hi:[1,1,1]
	v_pk_fma_f32 v[148:149], v[188:189], v[120:121], v[148:149] op_sel:[0,1,0] op_sel_hi:[1,1,1]
	v_pk_fma_f32 v[150:151], v[190:191], v[120:121], v[150:151] op_sel:[0,1,0] op_sel_hi:[1,1,1]
	v_pk_fma_f32 v[152:153], v[192:193], v[120:121], v[152:153] op_sel:[0,1,0] op_sel_hi:[1,1,1]
	v_pk_fma_f32 v[154:155], v[194:195], v[120:121], v[154:155] op_sel:[0,1,0] op_sel_hi:[1,1,1]
	v_pk_fma_f32 v[156:157], v[196:197], v[120:121], v[156:157] op_sel:[0,1,0] op_sel_hi:[1,1,1]
	v_pk_fma_f32 v[158:159], v[198:199], v[120:121], v[158:159] op_sel:[0,1,0] op_sel_hi:[1,1,1]
	s_waitcnt vmcnt(15)
	v_cvt_pk_f32_fp8_e32 v[184:185], v40
	v_cvt_pk_f32_fp8_sdwa v[186:187], v40 src0_sel:WORD_1
	v_cvt_pk_f32_fp8_e32 v[188:189], v41
	v_cvt_pk_f32_fp8_sdwa v[190:191], v41 src0_sel:WORD_1
	v_cvt_pk_f32_fp8_e32 v[192:193], v42
	v_cvt_pk_f32_fp8_sdwa v[194:195], v42 src0_sel:WORD_1
	v_cvt_pk_f32_fp8_e32 v[196:197], v43
	v_cvt_pk_f32_fp8_sdwa v[198:199], v43 src0_sel:WORD_1
	v_or_b32_e32 v218, v90, v203
	global_load_dwordx4 v[40:43], v218, s[44:45]
	v_pk_fma_f32 v[144:145], v[184:185], v[122:123], v[144:145] op_sel_hi:[1,0,1]
	v_pk_fma_f32 v[146:147], v[186:187], v[122:123], v[146:147] op_sel_hi:[1,0,1]
	v_pk_fma_f32 v[148:149], v[188:189], v[122:123], v[148:149] op_sel_hi:[1,0,1]
	v_pk_fma_f32 v[150:151], v[190:191], v[122:123], v[150:151] op_sel_hi:[1,0,1]
	v_pk_fma_f32 v[152:153], v[192:193], v[122:123], v[152:153] op_sel_hi:[1,0,1]
	v_pk_fma_f32 v[154:155], v[194:195], v[122:123], v[154:155] op_sel_hi:[1,0,1]
	v_pk_fma_f32 v[156:157], v[196:197], v[122:123], v[156:157] op_sel_hi:[1,0,1]
	v_pk_fma_f32 v[158:159], v[198:199], v[122:123], v[158:159] op_sel_hi:[1,0,1]
	s_waitcnt vmcnt(15)
	v_cvt_pk_f32_fp8_e32 v[184:185], v44
	v_cvt_pk_f32_fp8_sdwa v[186:187], v44 src0_sel:WORD_1
	v_cvt_pk_f32_fp8_e32 v[188:189], v45
	v_cvt_pk_f32_fp8_sdwa v[190:191], v45 src0_sel:WORD_1
	v_cvt_pk_f32_fp8_e32 v[192:193], v46
	v_cvt_pk_f32_fp8_sdwa v[194:195], v46 src0_sel:WORD_1
	v_cvt_pk_f32_fp8_e32 v[196:197], v47
	v_cvt_pk_f32_fp8_sdwa v[198:199], v47 src0_sel:WORD_1
	v_or_b32_e32 v218, v91, v203
	global_load_dwordx4 v[44:47], v218, s[44:45]
	v_pk_fma_f32 v[144:145], v[184:185], v[122:123], v[144:145] op_sel:[0,1,0] op_sel_hi:[1,1,1]
	v_pk_fma_f32 v[146:147], v[186:187], v[122:123], v[146:147] op_sel:[0,1,0] op_sel_hi:[1,1,1]
	v_pk_fma_f32 v[148:149], v[188:189], v[122:123], v[148:149] op_sel:[0,1,0] op_sel_hi:[1,1,1]
	v_pk_fma_f32 v[150:151], v[190:191], v[122:123], v[150:151] op_sel:[0,1,0] op_sel_hi:[1,1,1]
	v_pk_fma_f32 v[152:153], v[192:193], v[122:123], v[152:153] op_sel:[0,1,0] op_sel_hi:[1,1,1]
	v_pk_fma_f32 v[154:155], v[194:195], v[122:123], v[154:155] op_sel:[0,1,0] op_sel_hi:[1,1,1]
	v_pk_fma_f32 v[156:157], v[196:197], v[122:123], v[156:157] op_sel:[0,1,0] op_sel_hi:[1,1,1]
	v_pk_fma_f32 v[158:159], v[198:199], v[122:123], v[158:159] op_sel:[0,1,0] op_sel_hi:[1,1,1]
	s_waitcnt vmcnt(15)
	v_cvt_pk_f32_fp8_e32 v[184:185], v48
	v_cvt_pk_f32_fp8_sdwa v[186:187], v48 src0_sel:WORD_1
	v_cvt_pk_f32_fp8_e32 v[188:189], v49
	v_cvt_pk_f32_fp8_sdwa v[190:191], v49 src0_sel:WORD_1
	v_cvt_pk_f32_fp8_e32 v[192:193], v50
	v_cvt_pk_f32_fp8_sdwa v[194:195], v50 src0_sel:WORD_1
	v_cvt_pk_f32_fp8_e32 v[196:197], v51
	v_cvt_pk_f32_fp8_sdwa v[198:199], v51 src0_sel:WORD_1
	v_or_b32_e32 v218, v92, v203
	global_load_dwordx4 v[48:51], v218, s[44:45]
	v_pk_fma_f32 v[144:145], v[184:185], v[124:125], v[144:145] op_sel_hi:[1,0,1]
	v_pk_fma_f32 v[146:147], v[186:187], v[124:125], v[146:147] op_sel_hi:[1,0,1]
	v_pk_fma_f32 v[148:149], v[188:189], v[124:125], v[148:149] op_sel_hi:[1,0,1]
	v_pk_fma_f32 v[150:151], v[190:191], v[124:125], v[150:151] op_sel_hi:[1,0,1]
	v_pk_fma_f32 v[152:153], v[192:193], v[124:125], v[152:153] op_sel_hi:[1,0,1]
	v_pk_fma_f32 v[154:155], v[194:195], v[124:125], v[154:155] op_sel_hi:[1,0,1]
	v_pk_fma_f32 v[156:157], v[196:197], v[124:125], v[156:157] op_sel_hi:[1,0,1]
	v_pk_fma_f32 v[158:159], v[198:199], v[124:125], v[158:159] op_sel_hi:[1,0,1]
	s_waitcnt vmcnt(15)
; #define LAS __attribute__((address_space(3)))
; template <int Q> __device__ __forceinline__ void s9_pv(const unsigned (&vv)[8], LAS const float* ptw, int half, f32x2_t& oa, f32x2_t& ob) {
; #pragma unroll
;     for (int u2 = 0; u2 < 8; ++u2) { const float p = ptw[2 * (Q * 8 + u2) + half];
;         oa = __builtin_amdgcn_cvt_pk_f32_fp8((int)vv[u2], false) * p + oa; ob = __builtin_amdgcn_cvt_pk_f32_fp8((int)vv[u2], true) * p + ob; }
; }
	v_cvt_pk_f32_fp8_e32 v[184:185], v52
	v_cvt_pk_f32_fp8_sdwa v[186:187], v52 src0_sel:WORD_1
	v_cvt_pk_f32_fp8_e32 v[188:189], v53
	v_cvt_pk_f32_fp8_sdwa v[190:191], v53 src0_sel:WORD_1
	v_cvt_pk_f32_fp8_e32 v[192:193], v54
	v_cvt_pk_f32_fp8_sdwa v[194:195], v54 src0_sel:WORD_1
	v_cvt_pk_f32_fp8_e32 v[196:197], v55
	v_cvt_pk_f32_fp8_sdwa v[198:199], v55 src0_sel:WORD_1
	v_or_b32_e32 v218, v93, v203
	global_load_dwordx4 v[52:55], v218, s[44:45]
	v_pk_fma_f32 v[144:145], v[184:185], v[124:125], v[144:145] op_sel:[0,1,0] op_sel_hi:[1,1,1]
	v_pk_fma_f32 v[146:147], v[186:187], v[124:125], v[146:147] op_sel:[0,1,0] op_sel_hi:[1,1,1]
	v_pk_fma_f32 v[148:149], v[188:189], v[124:125], v[148:149] op_sel:[0,1,0] op_sel_hi:[1,1,1]
	v_pk_fma_f32 v[150:151], v[190:191], v[124:125], v[150:151] op_sel:[0,1,0] op_sel_hi:[1,1,1]
	v_pk_fma_f32 v[152:153], v[192:193], v[124:125], v[152:153] op_sel:[0,1,0] op_sel_hi:[1,1,1]
	v_pk_fma_f32 v[154:155], v[194:195], v[124:125], v[154:155] op_sel:[0,1,0] op_sel_hi:[1,1,1]
	v_pk_fma_f32 v[156:157], v[196:197], v[124:125], v[156:157] op_sel:[0,1,0] op_sel_hi:[1,1,1]
	v_pk_fma_f32 v[158:159], v[198:199], v[124:125], v[158:159] op_sel:[0,1,0] op_sel_hi:[1,1,1]
	s_waitcnt vmcnt(15)
	v_cvt_pk_f32_fp8_e32 v[184:185], v56
	v_cvt_pk_f32_fp8_sdwa v[186:187], v56 src0_sel:WORD_1
	v_cvt_pk_f32_fp8_e32 v[188:189], v57
	v_cvt_pk_f32_fp8_sdwa v[190:191], v57 src0_sel:WORD_1
	v_cvt_pk_f32_fp8_e32 v[192:193], v58
	v_cvt_pk_f32_fp8_sdwa v[194:195], v58 src0_sel:WORD_1
	v_cvt_pk_f32_fp8_e32 v[196:197], v59
	v_cvt_pk_f32_fp8_sdwa v[198:199], v59 src0_sel:WORD_1
	v_or_b32_e32 v218, v94, v203
	global_load_dwordx4 v[56:59], v218, s[44:45]
	v_pk_fma_f32 v[144:145], v[184:185], v[126:127], v[144:145] op_sel_hi:[1,0,1]
	v_pk_fma_f32 v[146:147], v[186:187], v[126:127], v[146:147] op_sel_hi:[1,0,1]
	v_pk_fma_f32 v[148:149], v[188:189], v[126:127], v[148:149] op_sel_hi:[1,0,1]
	v_pk_fma_f32 v[150:151], v[190:191], v[126:127], v[150:151] op_sel_hi:[1,0,1]
	v_pk_fma_f32 v[152:153], v[192:193], v[126:127], v[152:153] op_sel_hi:[1,0,1]
	v_pk_fma_f32 v[154:155], v[194:195], v[126:127], v[154:155] op_sel_hi:[1,0,1]
	v_pk_fma_f32 v[156:157], v[196:197], v[126:127], v[156:157] op_sel_hi:[1,0,1]
	v_pk_fma_f32 v[158:159], v[198:199], v[126:127], v[158:159] op_sel_hi:[1,0,1]
	s_waitcnt vmcnt(15)
	v_cvt_pk_f32_fp8_e32 v[184:185], v60
	v_cvt_pk_f32_fp8_sdwa v[186:187], v60 src0_sel:WORD_1
	v_cvt_pk_f32_fp8_e32 v[188:189], v61
	v_cvt_pk_f32_fp8_sdwa v[190:191], v61 src0_sel:WORD_1
	v_cvt_pk_f32_fp8_e32 v[192:193], v62
	v_cvt_pk_f32_fp8_sdwa v[194:195], v62 src0_sel:WORD_1
	v_cvt_pk_f32_fp8_e32 v[196:197], v63
	v_cvt_pk_f32_fp8_sdwa v[198:199], v63 src0_sel:WORD_1
	v_or_b32_e32 v218, v95, v203
	global_load_dwordx4 v[60:63], v218, s[44:45]
	v_pk_fma_f32 v[144:145], v[184:185], v[126:127], v[144:145] op_sel:[0,1,0] op_sel_hi:[1,1,1]
	v_pk_fma_f32 v[146:147], v[186:187], v[126:127], v[146:147] op_sel:[0,1,0] op_sel_hi:[1,1,1]
	v_pk_fma_f32 v[148:149], v[188:189], v[126:127], v[148:149] op_sel:[0,1,0] op_sel_hi:[1,1,1]
	v_pk_fma_f32 v[150:151], v[190:191], v[126:127], v[150:151] op_sel:[0,1,0] op_sel_hi:[1,1,1]
	v_pk_fma_f32 v[152:153], v[192:193], v[126:127], v[152:153] op_sel:[0,1,0] op_sel_hi:[1,1,1]
	v_pk_fma_f32 v[154:155], v[194:195], v[126:127], v[154:155] op_sel:[0,1,0] op_sel_hi:[1,1,1]
	v_pk_fma_f32 v[156:157], v[196:197], v[126:127], v[156:157] op_sel:[0,1,0] op_sel_hi:[1,1,1]
	v_pk_fma_f32 v[158:159], v[198:199], v[126:127], v[158:159] op_sel:[0,1,0] op_sel_hi:[1,1,1]
	ds_read_b128 v[112:115], v214 offset:64
	ds_read_b128 v[116:119], v214 offset:80
	ds_read_b128 v[120:123], v214 offset:96
	ds_read_b128 v[124:127], v214 offset:112
	s_waitcnt lgkmcnt(0)
	s_waitcnt vmcnt(15)
	v_cvt_pk_f32_fp8_e32 v[184:185], v0
	v_cvt_pk_f32_fp8_sdwa v[186:187], v0 src0_sel:WORD_1
	v_cvt_pk_f32_fp8_e32 v[188:189], v1
	v_cvt_pk_f32_fp8_sdwa v[190:191], v1 src0_sel:WORD_1
	v_cvt_pk_f32_fp8_e32 v[192:193], v2
	v_cvt_pk_f32_fp8_sdwa v[194:195], v2 src0_sel:WORD_1
	v_cvt_pk_f32_fp8_e32 v[196:197], v3
	v_cvt_pk_f32_fp8_sdwa v[198:199], v3 src0_sel:WORD_1
	v_pk_fma_f32 v[144:145], v[184:185], v[112:113], v[144:145] op_sel_hi:[1,0,1]
	v_pk_fma_f32 v[146:147], v[186:187], v[112:113], v[146:147] op_sel_hi:[1,0,1]
	v_pk_fma_f32 v[148:149], v[188:189], v[112:113], v[148:149] op_sel_hi:[1,0,1]
	v_pk_fma_f32 v[150:151], v[190:191], v[112:113], v[150:151] op_sel_hi:[1,0,1]
	v_pk_fma_f32 v[152:153], v[192:193], v[112:113], v[152:153] op_sel_hi:[1,0,1]
	v_pk_fma_f32 v[154:155], v[194:195], v[112:113], v[154:155] op_sel_hi:[1,0,1]
	v_pk_fma_f32 v[156:157], v[196:197], v[112:113], v[156:157] op_sel_hi:[1,0,1]
	v_pk_fma_f32 v[158:159], v[198:199], v[112:113], v[158:159] op_sel_hi:[1,0,1]
	s_waitcnt vmcnt(14)
	v_cvt_pk_f32_fp8_e32 v[184:185], v4
	v_cvt_pk_f32_fp8_sdwa v[186:187], v4 src0_sel:WORD_1
	v_cvt_pk_f32_fp8_e32 v[188:189], v5
	v_cvt_pk_f32_fp8_sdwa v[190:191], v5 src0_sel:WORD_1
	v_cvt_pk_f32_fp8_e32 v[192:193], v6
	v_cvt_pk_f32_fp8_sdwa v[194:195], v6 src0_sel:WORD_1
	v_cvt_pk_f32_fp8_e32 v[196:197], v7
	v_cvt_pk_f32_fp8_sdwa v[198:199], v7 src0_sel:WORD_1
	v_pk_fma_f32 v[144:145], v[184:185], v[112:113], v[144:145] op_sel:[0,1,0] op_sel_hi:[1,1,1]
	v_pk_fma_f32 v[146:147], v[186:187], v[112:113], v[146:147] op_sel:[0,1,0] op_sel_hi:[1,1,1]
	v_pk_fma_f32 v[148:149], v[188:189], v[112:113], v[148:149] op_sel:[0,1,0] op_sel_hi:[1,1,1]
	v_pk_fma_f32 v[150:151], v[190:191], v[112:113], v[150:151] op_sel:[0,1,0] op_sel_hi:[1,1,1]
	v_pk_fma_f32 v[152:153], v[192:193], v[112:113], v[152:153] op_sel:[0,1,0] op_sel_hi:[1,1,1]
	v_pk_fma_f32 v[154:155], v[194:195], v[112:113], v[154:155] op_sel:[0,1,0] op_sel_hi:[1,1,1]
	v_pk_fma_f32 v[156:157], v[196:197], v[112:113], v[156:157] op_sel:[0,1,0] op_sel_hi:[1,1,1]
	v_pk_fma_f32 v[158:159], v[198:199], v[112:113], v[158:159] op_sel:[0,1,0] op_sel_hi:[1,1,1]
	s_waitcnt vmcnt(13)
; #define LAS __attribute__((address_space(3)))
; template <int Q> __device__ __forceinline__ void s9_pv(const unsigned (&vv)[8], LAS const float* ptw, int half, f32x2_t& oa, f32x2_t& ob) {
; #pragma unroll
;     for (int u2 = 0; u2 < 8; ++u2) { const float p = ptw[2 * (Q * 8 + u2) + half];
;         oa = __builtin_amdgcn_cvt_pk_f32_fp8((int)vv[u2], false) * p + oa; ob = __builtin_amdgcn_cvt_pk_f32_fp8((int)vv[u2], true) * p + ob; }
; }
	v_cvt_pk_f32_fp8_e32 v[184:185], v8
	v_cvt_pk_f32_fp8_sdwa v[186:187], v8 src0_sel:WORD_1
	v_cvt_pk_f32_fp8_e32 v[188:189], v9
	v_cvt_pk_f32_fp8_sdwa v[190:191], v9 src0_sel:WORD_1
	v_cvt_pk_f32_fp8_e32 v[192:193], v10
	v_cvt_pk_f32_fp8_sdwa v[194:195], v10 src0_sel:WORD_1
	v_cvt_pk_f32_fp8_e32 v[196:197], v11
	v_cvt_pk_f32_fp8_sdwa v[198:199], v11 src0_sel:WORD_1
	v_pk_fma_f32 v[144:145], v[184:185], v[114:115], v[144:145] op_sel_hi:[1,0,1]
	v_pk_fma_f32 v[146:147], v[186:187], v[114:115], v[146:147] op_sel_hi:[1,0,1]
	v_pk_fma_f32 v[148:149], v[188:189], v[114:115], v[148:149] op_sel_hi:[1,0,1]
	v_pk_fma_f32 v[150:151], v[190:191], v[114:115], v[150:151] op_sel_hi:[1,0,1]
	v_pk_fma_f32 v[152:153], v[192:193], v[114:115], v[152:153] op_sel_hi:[1,0,1]
	v_pk_fma_f32 v[154:155], v[194:195], v[114:115], v[154:155] op_sel_hi:[1,0,1]
	v_pk_fma_f32 v[156:157], v[196:197], v[114:115], v[156:157] op_sel_hi:[1,0,1]
	v_pk_fma_f32 v[158:159], v[198:199], v[114:115], v[158:159] op_sel_hi:[1,0,1]
	s_waitcnt vmcnt(12)
	v_cvt_pk_f32_fp8_e32 v[184:185], v12
	v_cvt_pk_f32_fp8_sdwa v[186:187], v12 src0_sel:WORD_1
	v_cvt_pk_f32_fp8_e32 v[188:189], v13
	v_cvt_pk_f32_fp8_sdwa v[190:191], v13 src0_sel:WORD_1
	v_cvt_pk_f32_fp8_e32 v[192:193], v14
	v_cvt_pk_f32_fp8_sdwa v[194:195], v14 src0_sel:WORD_1
	v_cvt_pk_f32_fp8_e32 v[196:197], v15
	v_cvt_pk_f32_fp8_sdwa v[198:199], v15 src0_sel:WORD_1
	v_pk_fma_f32 v[144:145], v[184:185], v[114:115], v[144:145] op_sel:[0,1,0] op_sel_hi:[1,1,1]
	v_pk_fma_f32 v[146:147], v[186:187], v[114:115], v[146:147] op_sel:[0,1,0] op_sel_hi:[1,1,1]
	v_pk_fma_f32 v[148:149], v[188:189], v[114:115], v[148:149] op_sel:[0,1,0] op_sel_hi:[1,1,1]
	v_pk_fma_f32 v[150:151], v[190:191], v[114:115], v[150:151] op_sel:[0,1,0] op_sel_hi:[1,1,1]
	v_pk_fma_f32 v[152:153], v[192:193], v[114:115], v[152:153] op_sel:[0,1,0] op_sel_hi:[1,1,1]
	v_pk_fma_f32 v[154:155], v[194:195], v[114:115], v[154:155] op_sel:[0,1,0] op_sel_hi:[1,1,1]
	v_pk_fma_f32 v[156:157], v[196:197], v[114:115], v[156:157] op_sel:[0,1,0] op_sel_hi:[1,1,1]
	v_pk_fma_f32 v[158:159], v[198:199], v[114:115], v[158:159] op_sel:[0,1,0] op_sel_hi:[1,1,1]
	s_waitcnt vmcnt(11)
	v_cvt_pk_f32_fp8_e32 v[184:185], v16
	v_cvt_pk_f32_fp8_sdwa v[186:187], v16 src0_sel:WORD_1
	v_cvt_pk_f32_fp8_e32 v[188:189], v17
	v_cvt_pk_f32_fp8_sdwa v[190:191], v17 src0_sel:WORD_1
	v_cvt_pk_f32_fp8_e32 v[192:193], v18
	v_cvt_pk_f32_fp8_sdwa v[194:195], v18 src0_sel:WORD_1
	v_cvt_pk_f32_fp8_e32 v[196:197], v19
	v_cvt_pk_f32_fp8_sdwa v[198:199], v19 src0_sel:WORD_1
	v_pk_fma_f32 v[144:145], v[184:185], v[116:117], v[144:145] op_sel_hi:[1,0,1]
	v_pk_fma_f32 v[146:147], v[186:187], v[116:117], v[146:147] op_sel_hi:[1,0,1]
	v_pk_fma_f32 v[148:149], v[188:189], v[116:117], v[148:149] op_sel_hi:[1,0,1]
	v_pk_fma_f32 v[150:151], v[190:191], v[116:117], v[150:151] op_sel_hi:[1,0,1]
	v_pk_fma_f32 v[152:153], v[192:193], v[116:117], v[152:153] op_sel_hi:[1,0,1]
	v_pk_fma_f32 v[154:155], v[194:195], v[116:117], v[154:155] op_sel_hi:[1,0,1]
	v_pk_fma_f32 v[156:157], v[196:197], v[116:117], v[156:157] op_sel_hi:[1,0,1]
	v_pk_fma_f32 v[158:159], v[198:199], v[116:117], v[158:159] op_sel_hi:[1,0,1]
	s_waitcnt vmcnt(10)
	v_cvt_pk_f32_fp8_e32 v[184:185], v20
	v_cvt_pk_f32_fp8_sdwa v[186:187], v20 src0_sel:WORD_1
	v_cvt_pk_f32_fp8_e32 v[188:189], v21
	v_cvt_pk_f32_fp8_sdwa v[190:191], v21 src0_sel:WORD_1
	v_cvt_pk_f32_fp8_e32 v[192:193], v22
	v_cvt_pk_f32_fp8_sdwa v[194:195], v22 src0_sel:WORD_1
	v_cvt_pk_f32_fp8_e32 v[196:197], v23
	v_cvt_pk_f32_fp8_sdwa v[198:199], v23 src0_sel:WORD_1
	v_pk_fma_f32 v[144:145], v[184:185], v[116:117], v[144:145] op_sel:[0,1,0] op_sel_hi:[1,1,1]
	v_pk_fma_f32 v[146:147], v[186:187], v[116:117], v[146:147] op_sel:[0,1,0] op_sel_hi:[1,1,1]
	v_pk_fma_f32 v[148:149], v[188:189], v[116:117], v[148:149] op_sel:[0,1,0] op_sel_hi:[1,1,1]
	v_pk_fma_f32 v[150:151], v[190:191], v[116:117], v[150:151] op_sel:[0,1,0] op_sel_hi:[1,1,1]
	v_pk_fma_f32 v[152:153], v[192:193], v[116:117], v[152:153] op_sel:[0,1,0] op_sel_hi:[1,1,1]
	v_pk_fma_f32 v[154:155], v[194:195], v[116:117], v[154:155] op_sel:[0,1,0] op_sel_hi:[1,1,1]
	v_pk_fma_f32 v[156:157], v[196:197], v[116:117], v[156:157] op_sel:[0,1,0] op_sel_hi:[1,1,1]
	v_pk_fma_f32 v[158:159], v[198:199], v[116:117], v[158:159] op_sel:[0,1,0] op_sel_hi:[1,1,1]
	s_waitcnt vmcnt(9)
	v_cvt_pk_f32_fp8_e32 v[184:185], v24
	v_cvt_pk_f32_fp8_sdwa v[186:187], v24 src0_sel:WORD_1
	v_cvt_pk_f32_fp8_e32 v[188:189], v25
	v_cvt_pk_f32_fp8_sdwa v[190:191], v25 src0_sel:WORD_1
	v_cvt_pk_f32_fp8_e32 v[192:193], v26
	v_cvt_pk_f32_fp8_sdwa v[194:195], v26 src0_sel:WORD_1
	v_cvt_pk_f32_fp8_e32 v[196:197], v27
	v_cvt_pk_f32_fp8_sdwa v[198:199], v27 src0_sel:WORD_1
	v_pk_fma_f32 v[144:145], v[184:185], v[118:119], v[144:145] op_sel_hi:[1,0,1]
	v_pk_fma_f32 v[146:147], v[186:187], v[118:119], v[146:147] op_sel_hi:[1,0,1]
	v_pk_fma_f32 v[148:149], v[188:189], v[118:119], v[148:149] op_sel_hi:[1,0,1]
	v_pk_fma_f32 v[150:151], v[190:191], v[118:119], v[150:151] op_sel_hi:[1,0,1]
	v_pk_fma_f32 v[152:153], v[192:193], v[118:119], v[152:153] op_sel_hi:[1,0,1]
	v_pk_fma_f32 v[154:155], v[194:195], v[118:119], v[154:155] op_sel_hi:[1,0,1]
	v_pk_fma_f32 v[156:157], v[196:197], v[118:119], v[156:157] op_sel_hi:[1,0,1]
	v_pk_fma_f32 v[158:159], v[198:199], v[118:119], v[158:159] op_sel_hi:[1,0,1]
	s_waitcnt vmcnt(8)
; #define LAS __attribute__((address_space(3)))
; template <int Q> __device__ __forceinline__ void s9_pv(const unsigned (&vv)[8], LAS const float* ptw, int half, f32x2_t& oa, f32x2_t& ob) {
; #pragma unroll
;     for (int u2 = 0; u2 < 8; ++u2) { const float p = ptw[2 * (Q * 8 + u2) + half];
;         oa = __builtin_amdgcn_cvt_pk_f32_fp8((int)vv[u2], false) * p + oa; ob = __builtin_amdgcn_cvt_pk_f32_fp8((int)vv[u2], true) * p + ob; }
; }
	v_cvt_pk_f32_fp8_e32 v[184:185], v28
	v_cvt_pk_f32_fp8_sdwa v[186:187], v28 src0_sel:WORD_1
	v_cvt_pk_f32_fp8_e32 v[188:189], v29
	v_cvt_pk_f32_fp8_sdwa v[190:191], v29 src0_sel:WORD_1
	v_cvt_pk_f32_fp8_e32 v[192:193], v30
	v_cvt_pk_f32_fp8_sdwa v[194:195], v30 src0_sel:WORD_1
	v_cvt_pk_f32_fp8_e32 v[196:197], v31
	v_cvt_pk_f32_fp8_sdwa v[198:199], v31 src0_sel:WORD_1
	v_pk_fma_f32 v[144:145], v[184:185], v[118:119], v[144:145] op_sel:[0,1,0] op_sel_hi:[1,1,1]
	v_pk_fma_f32 v[146:147], v[186:187], v[118:119], v[146:147] op_sel:[0,1,0] op_sel_hi:[1,1,1]
	v_pk_fma_f32 v[148:149], v[188:189], v[118:119], v[148:149] op_sel:[0,1,0] op_sel_hi:[1,1,1]
	v_pk_fma_f32 v[150:151], v[190:191], v[118:119], v[150:151] op_sel:[0,1,0] op_sel_hi:[1,1,1]
	v_pk_fma_f32 v[152:153], v[192:193], v[118:119], v[152:153] op_sel:[0,1,0] op_sel_hi:[1,1,1]
	v_pk_fma_f32 v[154:155], v[194:195], v[118:119], v[154:155] op_sel:[0,1,0] op_sel_hi:[1,1,1]
	v_pk_fma_f32 v[156:157], v[196:197], v[118:119], v[156:157] op_sel:[0,1,0] op_sel_hi:[1,1,1]
	v_pk_fma_f32 v[158:159], v[198:199], v[118:119], v[158:159] op_sel:[0,1,0] op_sel_hi:[1,1,1]
	s_waitcnt vmcnt(7)
	v_cvt_pk_f32_fp8_e32 v[184:185], v32
	v_cvt_pk_f32_fp8_sdwa v[186:187], v32 src0_sel:WORD_1
	v_cvt_pk_f32_fp8_e32 v[188:189], v33
	v_cvt_pk_f32_fp8_sdwa v[190:191], v33 src0_sel:WORD_1
	v_cvt_pk_f32_fp8_e32 v[192:193], v34
	v_cvt_pk_f32_fp8_sdwa v[194:195], v34 src0_sel:WORD_1
	v_cvt_pk_f32_fp8_e32 v[196:197], v35
	v_cvt_pk_f32_fp8_sdwa v[198:199], v35 src0_sel:WORD_1
	v_pk_fma_f32 v[144:145], v[184:185], v[120:121], v[144:145] op_sel_hi:[1,0,1]
	v_pk_fma_f32 v[146:147], v[186:187], v[120:121], v[146:147] op_sel_hi:[1,0,1]
	v_pk_fma_f32 v[148:149], v[188:189], v[120:121], v[148:149] op_sel_hi:[1,0,1]
	v_pk_fma_f32 v[150:151], v[190:191], v[120:121], v[150:151] op_sel_hi:[1,0,1]
	v_pk_fma_f32 v[152:153], v[192:193], v[120:121], v[152:153] op_sel_hi:[1,0,1]
	v_pk_fma_f32 v[154:155], v[194:195], v[120:121], v[154:155] op_sel_hi:[1,0,1]
	v_pk_fma_f32 v[156:157], v[196:197], v[120:121], v[156:157] op_sel_hi:[1,0,1]
	v_pk_fma_f32 v[158:159], v[198:199], v[120:121], v[158:159] op_sel_hi:[1,0,1]
	s_waitcnt vmcnt(6)
	v_cvt_pk_f32_fp8_e32 v[184:185], v36
	v_cvt_pk_f32_fp8_sdwa v[186:187], v36 src0_sel:WORD_1
	v_cvt_pk_f32_fp8_e32 v[188:189], v37
	v_cvt_pk_f32_fp8_sdwa v[190:191], v37 src0_sel:WORD_1
	v_cvt_pk_f32_fp8_e32 v[192:193], v38
	v_cvt_pk_f32_fp8_sdwa v[194:195], v38 src0_sel:WORD_1
	v_cvt_pk_f32_fp8_e32 v[196:197], v39
	v_cvt_pk_f32_fp8_sdwa v[198:199], v39 src0_sel:WORD_1
	v_pk_fma_f32 v[144:145], v[184:185], v[120:121], v[144:145] op_sel:[0,1,0] op_sel_hi:[1,1,1]
	v_pk_fma_f32 v[146:147], v[186:187], v[120:121], v[146:147] op_sel:[0,1,0] op_sel_hi:[1,1,1]
	v_pk_fma_f32 v[148:149], v[188:189], v[120:121], v[148:149] op_sel:[0,1,0] op_sel_hi:[1,1,1]
	v_pk_fma_f32 v[150:151], v[190:191], v[120:121], v[150:151] op_sel:[0,1,0] op_sel_hi:[1,1,1]
	v_pk_fma_f32 v[152:153], v[192:193], v[120:121], v[152:153] op_sel:[0,1,0] op_sel_hi:[1,1,1]
	v_pk_fma_f32 v[154:155], v[194:195], v[120:121], v[154:155] op_sel:[0,1,0] op_sel_hi:[1,1,1]
	v_pk_fma_f32 v[156:157], v[196:197], v[120:121], v[156:157] op_sel:[0,1,0] op_sel_hi:[1,1,1]
	v_pk_fma_f32 v[158:159], v[198:199], v[120:121], v[158:159] op_sel:[0,1,0] op_sel_hi:[1,1,1]
	s_waitcnt vmcnt(5)
	v_cvt_pk_f32_fp8_e32 v[184:185], v40
	v_cvt_pk_f32_fp8_sdwa v[186:187], v40 src0_sel:WORD_1
	v_cvt_pk_f32_fp8_e32 v[188:189], v41
	v_cvt_pk_f32_fp8_sdwa v[190:191], v41 src0_sel:WORD_1
	v_cvt_pk_f32_fp8_e32 v[192:193], v42
	v_cvt_pk_f32_fp8_sdwa v[194:195], v42 src0_sel:WORD_1
	v_cvt_pk_f32_fp8_e32 v[196:197], v43
	v_cvt_pk_f32_fp8_sdwa v[198:199], v43 src0_sel:WORD_1
	v_pk_fma_f32 v[144:145], v[184:185], v[122:123], v[144:145] op_sel_hi:[1,0,1]
	v_pk_fma_f32 v[146:147], v[186:187], v[122:123], v[146:147] op_sel_hi:[1,0,1]
	v_pk_fma_f32 v[148:149], v[188:189], v[122:123], v[148:149] op_sel_hi:[1,0,1]
	v_pk_fma_f32 v[150:151], v[190:191], v[122:123], v[150:151] op_sel_hi:[1,0,1]
	v_pk_fma_f32 v[152:153], v[192:193], v[122:123], v[152:153] op_sel_hi:[1,0,1]
	v_pk_fma_f32 v[154:155], v[194:195], v[122:123], v[154:155] op_sel_hi:[1,0,1]
	v_pk_fma_f32 v[156:157], v[196:197], v[122:123], v[156:157] op_sel_hi:[1,0,1]
	v_pk_fma_f32 v[158:159], v[198:199], v[122:123], v[158:159] op_sel_hi:[1,0,1]
	s_waitcnt vmcnt(4)
	v_cvt_pk_f32_fp8_e32 v[184:185], v44
	v_cvt_pk_f32_fp8_sdwa v[186:187], v44 src0_sel:WORD_1
	v_cvt_pk_f32_fp8_e32 v[188:189], v45
	v_cvt_pk_f32_fp8_sdwa v[190:191], v45 src0_sel:WORD_1
	v_cvt_pk_f32_fp8_e32 v[192:193], v46
	v_cvt_pk_f32_fp8_sdwa v[194:195], v46 src0_sel:WORD_1
	v_cvt_pk_f32_fp8_e32 v[196:197], v47
	v_cvt_pk_f32_fp8_sdwa v[198:199], v47 src0_sel:WORD_1
	v_pk_fma_f32 v[144:145], v[184:185], v[122:123], v[144:145] op_sel:[0,1,0] op_sel_hi:[1,1,1]
	v_pk_fma_f32 v[146:147], v[186:187], v[122:123], v[146:147] op_sel:[0,1,0] op_sel_hi:[1,1,1]
	v_pk_fma_f32 v[148:149], v[188:189], v[122:123], v[148:149] op_sel:[0,1,0] op_sel_hi:[1,1,1]
	v_pk_fma_f32 v[150:151], v[190:191], v[122:123], v[150:151] op_sel:[0,1,0] op_sel_hi:[1,1,1]
	v_pk_fma_f32 v[152:153], v[192:193], v[122:123], v[152:153] op_sel:[0,1,0] op_sel_hi:[1,1,1]
	v_pk_fma_f32 v[154:155], v[194:195], v[122:123], v[154:155] op_sel:[0,1,0] op_sel_hi:[1,1,1]
	v_pk_fma_f32 v[156:157], v[196:197], v[122:123], v[156:157] op_sel:[0,1,0] op_sel_hi:[1,1,1]
	v_pk_fma_f32 v[158:159], v[198:199], v[122:123], v[158:159] op_sel:[0,1,0] op_sel_hi:[1,1,1]
	s_waitcnt vmcnt(3)
; #define LAS __attribute__((address_space(3)))
; template <int Q> __device__ __forceinline__ void s9_pv(const unsigned (&vv)[8], LAS const float* ptw, int half, f32x2_t& oa, f32x2_t& ob) {
; #pragma unroll
;     for (int u2 = 0; u2 < 8; ++u2) { const float p = ptw[2 * (Q * 8 + u2) + half];
;         oa = __builtin_amdgcn_cvt_pk_f32_fp8((int)vv[u2], false) * p + oa; ob = __builtin_amdgcn_cvt_pk_f32_fp8((int)vv[u2], true) * p + ob; }
; }
	v_cvt_pk_f32_fp8_e32 v[184:185], v48
	v_cvt_pk_f32_fp8_sdwa v[186:187], v48 src0_sel:WORD_1
	v_cvt_pk_f32_fp8_e32 v[188:189], v49
	v_cvt_pk_f32_fp8_sdwa v[190:191], v49 src0_sel:WORD_1
	v_cvt_pk_f32_fp8_e32 v[192:193], v50
	v_cvt_pk_f32_fp8_sdwa v[194:195], v50 src0_sel:WORD_1
	v_cvt_pk_f32_fp8_e32 v[196:197], v51
	v_cvt_pk_f32_fp8_sdwa v[198:199], v51 src0_sel:WORD_1
	v_pk_fma_f32 v[144:145], v[184:185], v[124:125], v[144:145] op_sel_hi:[1,0,1]
	v_pk_fma_f32 v[146:147], v[186:187], v[124:125], v[146:147] op_sel_hi:[1,0,1]
	v_pk_fma_f32 v[148:149], v[188:189], v[124:125], v[148:149] op_sel_hi:[1,0,1]
	v_pk_fma_f32 v[150:151], v[190:191], v[124:125], v[150:151] op_sel_hi:[1,0,1]
	v_pk_fma_f32 v[152:153], v[192:193], v[124:125], v[152:153] op_sel_hi:[1,0,1]
	v_pk_fma_f32 v[154:155], v[194:195], v[124:125], v[154:155] op_sel_hi:[1,0,1]
	v_pk_fma_f32 v[156:157], v[196:197], v[124:125], v[156:157] op_sel_hi:[1,0,1]
	v_pk_fma_f32 v[158:159], v[198:199], v[124:125], v[158:159] op_sel_hi:[1,0,1]
	s_waitcnt vmcnt(2)
	v_cvt_pk_f32_fp8_e32 v[184:185], v52
	v_cvt_pk_f32_fp8_sdwa v[186:187], v52 src0_sel:WORD_1
	v_cvt_pk_f32_fp8_e32 v[188:189], v53
	v_cvt_pk_f32_fp8_sdwa v[190:191], v53 src0_sel:WORD_1
	v_cvt_pk_f32_fp8_e32 v[192:193], v54
	v_cvt_pk_f32_fp8_sdwa v[194:195], v54 src0_sel:WORD_1
	v_cvt_pk_f32_fp8_e32 v[196:197], v55
	v_cvt_pk_f32_fp8_sdwa v[198:199], v55 src0_sel:WORD_1
	v_pk_fma_f32 v[144:145], v[184:185], v[124:125], v[144:145] op_sel:[0,1,0] op_sel_hi:[1,1,1]
	v_pk_fma_f32 v[146:147], v[186:187], v[124:125], v[146:147] op_sel:[0,1,0] op_sel_hi:[1,1,1]
	v_pk_fma_f32 v[148:149], v[188:189], v[124:125], v[148:149] op_sel:[0,1,0] op_sel_hi:[1,1,1]
	v_pk_fma_f32 v[150:151], v[190:191], v[124:125], v[150:151] op_sel:[0,1,0] op_sel_hi:[1,1,1]
	v_pk_fma_f32 v[152:153], v[192:193], v[124:125], v[152:153] op_sel:[0,1,0] op_sel_hi:[1,1,1]
	v_pk_fma_f32 v[154:155], v[194:195], v[124:125], v[154:155] op_sel:[0,1,0] op_sel_hi:[1,1,1]
	v_pk_fma_f32 v[156:157], v[196:197], v[124:125], v[156:157] op_sel:[0,1,0] op_sel_hi:[1,1,1]
	v_pk_fma_f32 v[158:159], v[198:199], v[124:125], v[158:159] op_sel:[0,1,0] op_sel_hi:[1,1,1]
	s_waitcnt vmcnt(1)
	v_cvt_pk_f32_fp8_e32 v[184:185], v56
	v_cvt_pk_f32_fp8_sdwa v[186:187], v56 src0_sel:WORD_1
	v_cvt_pk_f32_fp8_e32 v[188:189], v57
	v_cvt_pk_f32_fp8_sdwa v[190:191], v57 src0_sel:WORD_1
	v_cvt_pk_f32_fp8_e32 v[192:193], v58
	v_cvt_pk_f32_fp8_sdwa v[194:195], v58 src0_sel:WORD_1
	v_cvt_pk_f32_fp8_e32 v[196:197], v59
	v_cvt_pk_f32_fp8_sdwa v[198:199], v59 src0_sel:WORD_1
	v_pk_fma_f32 v[144:145], v[184:185], v[126:127], v[144:145] op_sel_hi:[1,0,1]
	v_pk_fma_f32 v[146:147], v[186:187], v[126:127], v[146:147] op_sel_hi:[1,0,1]
	v_pk_fma_f32 v[148:149], v[188:189], v[126:127], v[148:149] op_sel_hi:[1,0,1]
	v_pk_fma_f32 v[150:151], v[190:191], v[126:127], v[150:151] op_sel_hi:[1,0,1]
	v_pk_fma_f32 v[152:153], v[192:193], v[126:127], v[152:153] op_sel_hi:[1,0,1]
	v_pk_fma_f32 v[154:155], v[194:195], v[126:127], v[154:155] op_sel_hi:[1,0,1]
	v_pk_fma_f32 v[156:157], v[196:197], v[126:127], v[156:157] op_sel_hi:[1,0,1]
	v_pk_fma_f32 v[158:159], v[198:199], v[126:127], v[158:159] op_sel_hi:[1,0,1]
	s_waitcnt vmcnt(0)
; #define LAS __attribute__((address_space(3)))
; __device__ __forceinline__ unsigned pk2(float lo, float hi) { return f2bf(lo) | (f2bf(hi) << 16); }
; __device__ __forceinline__ float swap32_sum(float a, float b) { unsigned x, y; pl32(__builtin_bit_cast(unsigned, a), __builtin_bit_cast(unsigned, b), x, y); return __builtin_bit_cast(float, x) + __builtin_bit_cast(float, y); }
; template <int Q> __device__ __forceinline__ void s9_pv(const unsigned (&vv)[8], LAS const float* ptw, int half, f32x2_t& oa, f32x2_t& ob) {
; #pragma unroll
;     for (int u2 = 0; u2 < 8; ++u2) { const float p = ptw[2 * (Q * 8 + u2) + half];
;         oa = __builtin_amdgcn_cvt_pk_f32_fp8((int)vv[u2], false) * p + oa; ob = __builtin_amdgcn_cvt_pk_f32_fp8((int)vv[u2], true) * p + ob; }
; }
; __device__ __forceinline__ void sparse_unit7(const bf16_t* QKV, const unsigned char* K8, const unsigned char* V8, const int (&selv)[4], bf16_t* OB, LAS unsigned char* wl, int t, int h, int lane) {
;     ...
;     const float inv = 1.f / wave_sum(l);
;     const float r0 = swap32_sum(oa.x, oa.x), r1 = swap32_sum(oa.y, oa.y), r2 = swap32_sum(ob.x, ob.x), r3 = swap32_sum(ob.y, ob.y);
;     if (half == 0) { u32x2 o; o.x = pk2(r0 * inv, r1 * inv); o.y = pk2(r2 * inv, r3 * inv); *(u32x2*)(OB + (size_t)t * 1024 + h * 128 + l4) = o; }
	v_cvt_pk_f32_fp8_e32 v[184:185], v60
	v_cvt_pk_f32_fp8_sdwa v[186:187], v60 src0_sel:WORD_1
	v_cvt_pk_f32_fp8_e32 v[188:189], v61
	v_cvt_pk_f32_fp8_sdwa v[190:191], v61 src0_sel:WORD_1
	v_cvt_pk_f32_fp8_e32 v[192:193], v62
	v_cvt_pk_f32_fp8_sdwa v[194:195], v62 src0_sel:WORD_1
	v_cvt_pk_f32_fp8_e32 v[196:197], v63
	v_cvt_pk_f32_fp8_sdwa v[198:199], v63 src0_sel:WORD_1
	v_pk_fma_f32 v[144:145], v[184:185], v[126:127], v[144:145] op_sel:[0,1,0] op_sel_hi:[1,1,1]
	v_pk_fma_f32 v[146:147], v[186:187], v[126:127], v[146:147] op_sel:[0,1,0] op_sel_hi:[1,1,1]
	v_pk_fma_f32 v[148:149], v[188:189], v[126:127], v[148:149] op_sel:[0,1,0] op_sel_hi:[1,1,1]
	v_pk_fma_f32 v[150:151], v[190:191], v[126:127], v[150:151] op_sel:[0,1,0] op_sel_hi:[1,1,1]
	v_pk_fma_f32 v[152:153], v[192:193], v[126:127], v[152:153] op_sel:[0,1,0] op_sel_hi:[1,1,1]
	v_pk_fma_f32 v[154:155], v[194:195], v[126:127], v[154:155] op_sel:[0,1,0] op_sel_hi:[1,1,1]
	v_pk_fma_f32 v[156:157], v[196:197], v[126:127], v[156:157] op_sel:[0,1,0] op_sel_hi:[1,1,1]
	v_pk_fma_f32 v[158:159], v[198:199], v[126:127], v[158:159] op_sel:[0,1,0] op_sel_hi:[1,1,1]
	v_rcp_f32_e32 v218, v246
	s_nop 1
	v_fma_f32 v219, -v246, v218, 1.0
	v_fma_f32 v218, v219, v218, v218
	v_add_f32_dpp v144, v144, v144 row_ror:8 row_mask:0xf bank_mask:0xf bound_ctrl:1
	v_add_f32_dpp v145, v145, v145 row_ror:8 row_mask:0xf bank_mask:0xf bound_ctrl:1
	v_add_f32_dpp v146, v146, v146 row_ror:8 row_mask:0xf bank_mask:0xf bound_ctrl:1
	v_add_f32_dpp v147, v147, v147 row_ror:8 row_mask:0xf bank_mask:0xf bound_ctrl:1
	v_add_f32_dpp v148, v148, v148 row_ror:8 row_mask:0xf bank_mask:0xf bound_ctrl:1
	v_add_f32_dpp v149, v149, v149 row_ror:8 row_mask:0xf bank_mask:0xf bound_ctrl:1
	v_add_f32_dpp v150, v150, v150 row_ror:8 row_mask:0xf bank_mask:0xf bound_ctrl:1
	v_add_f32_dpp v151, v151, v151 row_ror:8 row_mask:0xf bank_mask:0xf bound_ctrl:1
	v_add_f32_dpp v152, v152, v152 row_ror:8 row_mask:0xf bank_mask:0xf bound_ctrl:1
	v_add_f32_dpp v153, v153, v153 row_ror:8 row_mask:0xf bank_mask:0xf bound_ctrl:1
	v_add_f32_dpp v154, v154, v154 row_ror:8 row_mask:0xf bank_mask:0xf bound_ctrl:1
	v_add_f32_dpp v155, v155, v155 row_ror:8 row_mask:0xf bank_mask:0xf bound_ctrl:1
	v_add_f32_dpp v156, v156, v156 row_ror:8 row_mask:0xf bank_mask:0xf bound_ctrl:1
	v_add_f32_dpp v157, v157, v157 row_ror:8 row_mask:0xf bank_mask:0xf bound_ctrl:1
	v_add_f32_dpp v158, v158, v158 row_ror:8 row_mask:0xf bank_mask:0xf bound_ctrl:1
	v_add_f32_dpp v159, v159, v159 row_ror:8 row_mask:0xf bank_mask:0xf bound_ctrl:1
	s_nop 1
	v_permlane16_swap_b32_e32 v144, v148
	v_permlane16_swap_b32_e32 v145, v149
	v_permlane16_swap_b32_e32 v146, v150
	v_permlane16_swap_b32_e32 v147, v151
	v_permlane16_swap_b32_e32 v152, v156
	v_permlane16_swap_b32_e32 v153, v157
	v_permlane16_swap_b32_e32 v154, v158
	v_permlane16_swap_b32_e32 v155, v159
	s_nop 1
	v_add_f32_e32 v144, v144, v148
	v_add_f32_e32 v145, v145, v149
	v_add_f32_e32 v146, v146, v150
	v_add_f32_e32 v147, v147, v151
	v_add_f32_e32 v152, v152, v156
	v_add_f32_e32 v153, v153, v157
	v_add_f32_e32 v154, v154, v158
	v_add_f32_e32 v155, v155, v159
	s_nop 1
	v_permlane32_swap_b32_e32 v144, v152
	v_permlane32_swap_b32_e32 v145, v153
	v_permlane32_swap_b32_e32 v146, v154
	v_permlane32_swap_b32_e32 v147, v155
	s_nop 1
	v_add_f32_e32 v144, v144, v152
	v_add_f32_e32 v145, v145, v153
	v_add_f32_e32 v146, v146, v154
	v_add_f32_e32 v147, v147, v155
	v_mul_f32_e32 v144, v144, v218
	v_mul_f32_e32 v145, v145, v218
	v_mul_f32_e32 v146, v146, v218
	v_mul_f32_e32 v147, v147, v218
	v_cvt_pk_bf16_f32 v246, v144, v145
	v_cvt_pk_bf16_f32 v247, v146, v147
	s_lshl_b32 s0, s34, 11
	s_add_u32 s0, s46, s0
	s_addc_u32 s1, s47, 0
	s_mov_b64 s[4:5], exec
	s_mov_b32 exec_lo, 0x00ff00ff
	s_mov_b32 exec_hi, 0x00ff00ff
	global_store_dwordx2 v215, v[246:247], s[0:1]
	s_mov_b64 exec, s[4:5]
	s_add_i32 s34, s34, s48
	s_cmpk_lt_i32 s34, 0x4000
	s_cbranch_scc1 .Lsp_unit
	s_waitcnt vmcnt(0)
	s_branch .LBB0_190
